# hoist post-MFMA SALU/VALU tail into MFMA gaps in GEMM loops (on top of E1 + XCD-local barriers)
# speedup vs baseline: 1.0268x; 1.0042x over previous
.LBB0_384:
	s_add_u32 s54, s42, 0xfffd0080
	s_addc_u32 s55, s43, -1
	s_add_i32 s70, 0, 0x10000
	v_add_u32_e32 v96, s70, v157
	ds_read_b128 v[160:163], v96
	ds_read_b128 v[164:167], v96 offset:1024
	ds_read_b128 v[168:171], v96 offset:2048
	ds_read_b128 v[172:175], v96 offset:3072
	s_cmp_eq_u32 s69, 12
	s_cselect_b32 s57, s51, s55
	s_cselect_b32 s56, s50, s54
	s_cselect_b32 s55, s49, s68
	s_cselect_b32 s54, s66, s67
	v_lshl_add_u64 v[154:155], s[42:43], 0, v[150:151]
	s_add_i32 m0, s28, 0xc000
	ds_read_b128 v[182:185], v159
	ds_read_b128 v[186:189], v159 offset:1024
	ds_read_b128 v[190:193], v159 offset:2048
	ds_read_b128 v[194:197], v159 offset:3072
	ds_read_b128 v[198:201], v159 offset:4096
	ds_read_b128 v[224:227], v159 offset:5120
	global_load_lds_dwordx4 v[154:155], off
	v_lshl_add_u64 v[154:155], s[42:43], 0, v[152:153]
	s_add_i32 m0, s28, 0xe000
	s_mov_b64 exec, s[98:99]
	global_load_lds_dwordx4 v[154:155], off
	s_mov_b64 exec, -1
	s_waitcnt lgkmcnt(8)
	s_barrier
	s_waitcnt lgkmcnt(0)
	s_setprio 1
	s_waitcnt lgkmcnt(0)
	v_mfma_f32_16x16x32_bf16 v[134:137], v[160:163], v[182:185], v[134:137]
	v_mfma_f32_16x16x32_bf16 v[130:133], v[168:171], v[182:185], v[130:133]
	v_mfma_f32_16x16x32_bf16 v[118:121], v[160:163], v[190:193], v[118:121]
	v_mfma_f32_16x16x32_bf16 v[114:117], v[168:171], v[190:193], v[114:117]
	v_mfma_f32_16x16x32_bf16 v[102:105], v[160:163], v[198:201], v[102:105]
	v_mfma_f32_16x16x32_bf16 v[98:101], v[168:171], v[198:201], v[98:101]
	v_mfma_f32_16x16x32_bf16 v[134:137], v[164:167], v[186:189], v[134:137]
	v_mfma_f32_16x16x32_bf16 v[130:133], v[172:175], v[186:189], v[130:133]
	v_mfma_f32_16x16x32_bf16 v[118:121], v[164:167], v[194:197], v[118:121]
	v_mfma_f32_16x16x32_bf16 v[114:117], v[172:175], v[194:197], v[114:117]
	v_mfma_f32_16x16x32_bf16 v[102:105], v[164:167], v[224:227], v[102:105]
	v_mfma_f32_16x16x32_bf16 v[98:101], v[172:175], v[224:227], v[98:101]
	s_setprio 0
	s_barrier
	s_add_i32 s72, 0, 0x14000
	s_add_i32 s70, s70, s18
	v_add_u32_e32 v96, s72, v157
	v_lshl_add_u64 v[154:155], s[54:55], 0, v[142:143]
	s_mov_b32 m0, s70
	ds_read_b128 v[228:231], v96
	ds_read_b128 v[232:235], v96 offset:1024
	ds_read_b128 v[236:239], v96 offset:2048
	ds_read_b128 v[240:243], v96 offset:3072
	global_load_lds_dwordx4 v[154:155], off
	v_lshl_add_u64 v[176:177], s[54:55], 0, v[138:139]
	s_add_i32 m0, s70, 0x2000
	s_nop 0
	global_load_lds_dwordx4 v[176:177], off
	s_barrier
	s_waitcnt lgkmcnt(0)
	s_setprio 1
	s_waitcnt lgkmcnt(0)
	v_mfma_f32_16x16x32_bf16 v[126:129], v[228:231], v[182:185], v[126:129]
	v_mfma_f32_16x16x32_bf16 v[122:125], v[236:239], v[182:185], v[122:125]
	v_mfma_f32_16x16x32_bf16 v[110:113], v[228:231], v[190:193], v[110:113]
	s_mov_b32 m0, s28
	v_mfma_f32_16x16x32_bf16 v[106:109], v[236:239], v[190:193], v[106:109]
	v_lshl_add_u64 v[202:203], s[56:57], 0, v[144:145]
	v_mfma_f32_16x16x32_bf16 v[92:95], v[228:231], v[198:201], v[92:95]
	v_mfma_f32_16x16x32_bf16 v[88:91], v[236:239], v[198:201], v[88:91]
	v_mfma_f32_16x16x32_bf16 v[126:129], v[232:235], v[186:189], v[126:129]
	v_mfma_f32_16x16x32_bf16 v[122:125], v[240:243], v[186:189], v[122:125]
	v_mfma_f32_16x16x32_bf16 v[110:113], v[232:235], v[194:197], v[110:113]
	v_mfma_f32_16x16x32_bf16 v[106:109], v[240:243], v[194:197], v[106:109]
	v_mfma_f32_16x16x32_bf16 v[92:95], v[232:235], v[224:227], v[92:95]
	v_mfma_f32_16x16x32_bf16 v[88:91], v[240:243], v[224:227], v[88:91]
	s_setprio 0
	s_barrier
	ds_read_b128 v[182:185], v159 offset:16384
	ds_read_b128 v[186:189], v159 offset:17408
	ds_read_b128 v[190:193], v159 offset:18432
	ds_read_b128 v[194:197], v159 offset:19456
	ds_read_b128 v[198:201], v159 offset:20480
	ds_read_b128 v[224:227], v159 offset:21504
	global_load_lds_dwordx4 v[202:203], off
	v_lshl_add_u64 v[244:245], s[56:57], 0, v[140:141]
	s_mov_b32 m0, s37
	s_mov_b64 exec, s[98:99]
	global_load_lds_dwordx4 v[244:245], off
	s_mov_b64 exec, -1
	s_barrier
	s_waitcnt lgkmcnt(0)
	s_setprio 1
	s_waitcnt lgkmcnt(0)
	v_mfma_f32_16x16x32_bf16 v[84:87], v[160:163], v[182:185], v[84:87]
	v_mfma_f32_16x16x32_bf16 v[80:83], v[168:171], v[182:185], v[80:83]
	v_mfma_f32_16x16x32_bf16 v[68:71], v[160:163], v[190:193], v[68:71]
	v_mfma_f32_16x16x32_bf16 v[64:67], v[168:171], v[190:193], v[64:67]
	v_mfma_f32_16x16x32_bf16 v[28:31], v[160:163], v[198:201], v[28:31]
	v_mfma_f32_16x16x32_bf16 v[24:27], v[168:171], v[198:201], v[24:27]
	v_mfma_f32_16x16x32_bf16 v[84:87], v[164:167], v[186:189], v[84:87]
	v_mfma_f32_16x16x32_bf16 v[80:83], v[172:175], v[186:189], v[80:83]
	v_mfma_f32_16x16x32_bf16 v[68:71], v[164:167], v[194:197], v[68:71]
	v_mfma_f32_16x16x32_bf16 v[64:67], v[172:175], v[194:197], v[64:67]
	v_mfma_f32_16x16x32_bf16 v[28:31], v[164:167], v[224:227], v[28:31]
	v_mfma_f32_16x16x32_bf16 v[24:27], v[172:175], v[224:227], v[24:27]
	s_setprio 0
	s_barrier
	s_add_u32 s70, s54, 0x40000
	s_addc_u32 s71, s55, 0
	s_add_i32 s72, s72, s18
	v_lshl_add_u64 v[160:161], s[70:71], 0, v[142:143]
	s_mov_b32 m0, s72
	s_nop 0
	global_load_lds_dwordx4 v[160:161], off
	v_lshl_add_u64 v[160:161], s[70:71], 0, v[138:139]
	s_add_i32 m0, s72, 0x2000
	s_nop 0
	global_load_lds_dwordx4 v[160:161], off
	s_waitcnt vmcnt(6)
	s_barrier
	s_setprio 1
	v_mfma_f32_16x16x32_bf16 v[76:79], v[228:231], v[182:185], v[76:79]
	v_mfma_f32_16x16x32_bf16 v[72:75], v[236:239], v[182:185], v[72:75]
	v_mfma_f32_16x16x32_bf16 v[60:63], v[228:231], v[190:193], v[60:63]
	s_add_i32 s70, 0, 0x18000
	v_mfma_f32_16x16x32_bf16 v[56:59], v[236:239], v[190:193], v[56:59]
	v_add_u32_e32 v96, s70, v157
	v_mfma_f32_16x16x32_bf16 v[20:23], v[228:231], v[198:201], v[20:23]
	v_mfma_f32_16x16x32_bf16 v[16:19], v[236:239], v[198:201], v[16:19]
	v_mfma_f32_16x16x32_bf16 v[76:79], v[232:235], v[186:189], v[76:79]
	v_mfma_f32_16x16x32_bf16 v[72:75], v[240:243], v[186:189], v[72:75]
	v_mfma_f32_16x16x32_bf16 v[60:63], v[232:235], v[194:197], v[60:63]
	v_mfma_f32_16x16x32_bf16 v[56:59], v[240:243], v[194:197], v[56:59]
	v_mfma_f32_16x16x32_bf16 v[20:23], v[232:235], v[224:227], v[20:23]
	v_mfma_f32_16x16x32_bf16 v[16:19], v[240:243], v[224:227], v[16:19]
	s_setprio 0
	s_barrier
	ds_read_b128 v[160:163], v96
	ds_read_b128 v[164:167], v96 offset:1024
	ds_read_b128 v[168:171], v96 offset:2048
	ds_read_b128 v[172:175], v96 offset:3072
	s_add_u32 s56, s56, 0x30000
	s_addc_u32 s57, s57, 0
	s_mov_b32 m0, s58
	v_lshl_add_u64 v[228:229], s[56:57], 0, v[144:145]
	ds_read_b128 v[182:185], v159 offset:32768
	ds_read_b128 v[186:189], v159 offset:33792
	ds_read_b128 v[190:193], v159 offset:34816
	ds_read_b128 v[194:197], v159 offset:35840
	ds_read_b128 v[198:201], v159 offset:36864
	ds_read_b128 v[224:227], v159 offset:37888
	global_load_lds_dwordx4 v[228:229], off
	v_lshl_add_u64 v[228:229], s[56:57], 0, v[140:141]
	s_mov_b32 m0, s59
	s_mov_b64 exec, s[98:99]
	global_load_lds_dwordx4 v[228:229], off
	s_mov_b64 exec, -1
	s_waitcnt lgkmcnt(8)
	s_barrier
	s_waitcnt lgkmcnt(0)
	s_setprio 1
	s_waitcnt lgkmcnt(0)
	v_mfma_f32_16x16x32_bf16 v[134:137], v[160:163], v[182:185], v[134:137]
	v_mfma_f32_16x16x32_bf16 v[130:133], v[168:171], v[182:185], v[130:133]
	v_mfma_f32_16x16x32_bf16 v[118:121], v[160:163], v[190:193], v[118:121]
	v_mfma_f32_16x16x32_bf16 v[114:117], v[168:171], v[190:193], v[114:117]
	v_mfma_f32_16x16x32_bf16 v[102:105], v[160:163], v[198:201], v[102:105]
	v_mfma_f32_16x16x32_bf16 v[98:101], v[168:171], v[198:201], v[98:101]
	v_mfma_f32_16x16x32_bf16 v[134:137], v[164:167], v[186:189], v[134:137]
	v_mfma_f32_16x16x32_bf16 v[130:133], v[172:175], v[186:189], v[130:133]
	v_mfma_f32_16x16x32_bf16 v[118:121], v[164:167], v[194:197], v[118:121]
	v_mfma_f32_16x16x32_bf16 v[114:117], v[172:175], v[194:197], v[114:117]
	v_mfma_f32_16x16x32_bf16 v[102:105], v[164:167], v[224:227], v[102:105]
	v_mfma_f32_16x16x32_bf16 v[98:101], v[172:175], v[224:227], v[98:101]
	s_setprio 0
	s_barrier
	s_add_i32 s56, 0, 0x1c000
	s_add_i32 s57, s70, s18
	v_add_u32_e32 v96, s56, v157
	v_lshl_add_u64 v[154:155], v[154:155], 0, s[6:7]
	s_mov_b32 m0, s57
	ds_read_b128 v[228:231], v96
	ds_read_b128 v[232:235], v96 offset:1024
	ds_read_b128 v[236:239], v96 offset:2048
	ds_read_b128 v[240:243], v96 offset:3072
	global_load_lds_dwordx4 v[154:155], off
	v_lshl_add_u64 v[154:155], v[176:177], 0, s[6:7]
	s_add_i32 m0, s57, 0x2000
	s_nop 0
	global_load_lds_dwordx4 v[154:155], off
	s_barrier
	s_waitcnt lgkmcnt(0)
	s_setprio 1
	s_waitcnt lgkmcnt(0)
	v_mfma_f32_16x16x32_bf16 v[126:129], v[228:231], v[182:185], v[126:129]
	v_mfma_f32_16x16x32_bf16 v[122:125], v[236:239], v[182:185], v[122:125]
	v_mfma_f32_16x16x32_bf16 v[110:113], v[228:231], v[190:193], v[110:113]
	s_mov_b32 m0, s60
	v_mfma_f32_16x16x32_bf16 v[106:109], v[236:239], v[190:193], v[106:109]
	v_lshl_add_u64 v[154:155], v[202:203], 0, s[6:7]
	v_mfma_f32_16x16x32_bf16 v[92:95], v[228:231], v[198:201], v[92:95]
	v_mfma_f32_16x16x32_bf16 v[88:91], v[236:239], v[198:201], v[88:91]
	v_mfma_f32_16x16x32_bf16 v[126:129], v[232:235], v[186:189], v[126:129]
	v_mfma_f32_16x16x32_bf16 v[122:125], v[240:243], v[186:189], v[122:125]
	v_mfma_f32_16x16x32_bf16 v[110:113], v[232:235], v[194:197], v[110:113]
	v_mfma_f32_16x16x32_bf16 v[106:109], v[240:243], v[194:197], v[106:109]
	v_mfma_f32_16x16x32_bf16 v[92:95], v[232:235], v[224:227], v[92:95]
	v_mfma_f32_16x16x32_bf16 v[88:91], v[240:243], v[224:227], v[88:91]
	s_setprio 0
	s_barrier
	ds_read_b128 v[182:185], v159 offset:49152
	ds_read_b128 v[186:189], v159 offset:50176
	ds_read_b128 v[190:193], v159 offset:51200
	ds_read_b128 v[194:197], v159 offset:52224
	ds_read_b128 v[198:201], v159 offset:53248
	ds_read_b128 v[224:227], v159 offset:54272
	global_load_lds_dwordx4 v[154:155], off
	v_lshl_add_u64 v[154:155], v[244:245], 0, s[6:7]
	s_mov_b32 m0, s61
	s_mov_b64 exec, s[98:99]
	global_load_lds_dwordx4 v[154:155], off
	s_mov_b64 exec, -1
	s_barrier
	s_waitcnt lgkmcnt(0)
	s_setprio 1
	s_waitcnt lgkmcnt(0)
	v_mfma_f32_16x16x32_bf16 v[84:87], v[160:163], v[182:185], v[84:87]
	v_mfma_f32_16x16x32_bf16 v[80:83], v[168:171], v[182:185], v[80:83]
	v_mfma_f32_16x16x32_bf16 v[68:71], v[160:163], v[190:193], v[68:71]
	v_mfma_f32_16x16x32_bf16 v[64:67], v[168:171], v[190:193], v[64:67]
	v_mfma_f32_16x16x32_bf16 v[28:31], v[160:163], v[198:201], v[28:31]
	v_mfma_f32_16x16x32_bf16 v[24:27], v[168:171], v[198:201], v[24:27]
	v_mfma_f32_16x16x32_bf16 v[84:87], v[164:167], v[186:189], v[84:87]
	v_mfma_f32_16x16x32_bf16 v[80:83], v[172:175], v[186:189], v[80:83]
	v_mfma_f32_16x16x32_bf16 v[68:71], v[164:167], v[194:197], v[68:71]
	v_mfma_f32_16x16x32_bf16 v[64:67], v[172:175], v[194:197], v[64:67]
	v_mfma_f32_16x16x32_bf16 v[28:31], v[164:167], v[224:227], v[28:31]
	v_mfma_f32_16x16x32_bf16 v[24:27], v[172:175], v[224:227], v[24:27]
	s_setprio 0
	s_barrier
	s_add_u32 s54, s54, 0x40080
	s_addc_u32 s55, s55, 0
	s_add_i32 s56, s56, s18
	v_lshl_add_u64 v[154:155], s[54:55], 0, v[142:143]
	s_mov_b32 m0, s56
	s_nop 0
	global_load_lds_dwordx4 v[154:155], off
	v_lshl_add_u64 v[154:155], s[54:55], 0, v[138:139]
	s_add_i32 m0, s56, 0x2000
	s_nop 0
	global_load_lds_dwordx4 v[154:155], off
	s_waitcnt vmcnt(6)
	s_barrier
	s_setprio 1
	v_mfma_f32_16x16x32_bf16 v[76:79], v[228:231], v[182:185], v[76:79]
	v_mfma_f32_16x16x32_bf16 v[72:75], v[236:239], v[182:185], v[72:75]
	v_mfma_f32_16x16x32_bf16 v[60:63], v[228:231], v[190:193], v[60:63]
	s_add_i32 s69, s69, 2
	v_mfma_f32_16x16x32_bf16 v[56:59], v[236:239], v[190:193], v[56:59]
	s_add_u32 s42, s42, 0x100
	v_mfma_f32_16x16x32_bf16 v[20:23], v[228:231], v[198:201], v[20:23]
	s_addc_u32 s43, s43, 0
	v_mfma_f32_16x16x32_bf16 v[16:19], v[236:239], v[198:201], v[16:19]
	s_add_u32 s67, s67, 0x100
	v_mfma_f32_16x16x32_bf16 v[76:79], v[232:235], v[186:189], v[76:79]
	s_addc_u32 s68, s68, 0
	v_mfma_f32_16x16x32_bf16 v[72:75], v[240:243], v[186:189], v[72:75]
	s_cmp_gt_u32 s69, 13
	v_mfma_f32_16x16x32_bf16 v[60:63], v[232:235], v[194:197], v[60:63]
	v_mfma_f32_16x16x32_bf16 v[56:59], v[240:243], v[194:197], v[56:59]
	v_mfma_f32_16x16x32_bf16 v[20:23], v[232:235], v[224:227], v[20:23]
	v_mfma_f32_16x16x32_bf16 v[16:19], v[240:243], v[224:227], v[16:19]
	s_setprio 0
	s_barrier
	s_cbranch_scc0 .LBB0_384
	s_waitcnt vmcnt(0)
	v_add_f32_e32 v52, v52, v53
	v_add_f32_e32 v53, v54, v55
	v_add_f32_e32 v52, v52, v53
	v_mov_b32_e32 v53, v52
	s_nop 1
	v_permlane16_swap_b32_e32 v52, v53
	v_add_f32_e32 v52, v52, v53
	v_mov_b32_e32 v53, v52
	s_nop 1
	v_permlane32_swap_b32_e32 v52, v53
	v_add_f32_e32 v52, v52, v53
	v_fmamk_f32 v52, v52, 0x3a800000, v207
	s_mul_i32 s42, s65, 0xc0
	v_rsq_f32_e32 v52, v52
	v_add_f32_e32 v36, v36, v37
	v_add_f32_e32 v37, v38, v39
	s_add_i32 s42, s42, s19
	v_add_f32_e32 v44, v44, v45
	v_add_f32_e32 v45, v46, v47
	v_add_f32_e32 v36, v36, v37
	s_cmpk_lt_u32 s42, 0x2000
	v_add_f32_e32 v44, v44, v45
	v_mov_b32_e32 v37, v36
	v_lshl_or_b32 v154, s64, 8, v158
	s_cselect_b32 s43, 1, 2
	v_or_b32_e32 v160, s42, v156
	v_mov_b32_e32 v45, v44
	v_permlane16_swap_b32_e32 v36, v37
	v_add_f32_e32 v32, v32, v33
	v_add_f32_e32 v33, v34, v35
	v_mov_b64_e32 v[34:35], s[46:47]
	v_mov_b32_e32 v96, s43
	v_permlane16_swap_b32_e32 v44, v45
	v_add_f32_e32 v38, v36, v37
	v_add_f32_e32 v36, v40, v41
	v_add_f32_e32 v37, v42, v43
	v_ashrrev_i32_e32 v155, 31, v154
	v_mad_i64_i32 v[34:35], s[42:43], v160, s25, v[34:35]
	v_pk_fma_f32 v[42:43], v[136:137], v[52:53], v[6:7] op_sel_hi:[1,0,1]
	v_pk_fma_f32 v[40:41], v[134:135], v[52:53], v[4:5] op_sel_hi:[1,0,1]
	v_add_f32_e32 v46, v44, v45
	v_add_f32_e32 v44, v48, v49
	v_add_f32_e32 v45, v50, v51
	v_lshl_add_u64 v[34:35], v[154:155], 1, v[34:35]
	v_pk_fma_f32 v[48:49], v[132:133], v[52:53], v[2:3] op_sel_hi:[1,0,1]
	v_pk_fma_f32 v[50:51], v[130:131], v[52:53], v[0:1] op_sel_hi:[1,0,1]
	v_cvt_pk_bf16_f32 v40, v40, v41
	v_cvt_pk_bf16_f32 v41, v42, v43
	v_add_f32_e32 v44, v44, v45
	v_cvt_pk_bf16_f32 v42, v50, v51
	v_cvt_pk_bf16_f32 v43, v48, v49
	v_add_f32_e32 v36, v36, v37
	v_add_f32_e32 v32, v32, v33
	global_store_dwordx4 v[34:35], v[40:43], off
	v_cmp_lt_i32_e32 vcc, s23, v160
	v_mov_b32_e32 v45, v44
	v_pk_fma_f32 v[42:43], v[128:129], v[52:53], v[14:15] op_sel_hi:[1,0,1]
	v_pk_fma_f32 v[40:41], v[126:127], v[52:53], v[12:13] op_sel_hi:[1,0,1]
	v_mov_b32_e32 v37, v36
	v_mov_b32_e32 v33, v32
	v_pk_fma_f32 v[48:49], v[124:125], v[52:53], v[10:11] op_sel_hi:[1,0,1]
	v_pk_fma_f32 v[50:51], v[122:123], v[52:53], v[8:9] op_sel_hi:[1,0,1]
	v_cvt_pk_bf16_f32 v40, v40, v41
	v_cvt_pk_bf16_f32 v41, v42, v43
	v_cndmask_b32_e32 v96, 0, v96, vcc
	v_cvt_pk_bf16_f32 v42, v50, v51
	v_cvt_pk_bf16_f32 v43, v48, v49
	global_store_dwordx4 v[34:35], v[40:43], off offset:256
	v_add_u32_e32 v34, 16, v160
	v_permlane16_swap_b32_e32 v44, v45
	v_permlane16_swap_b32_e32 v36, v37
	v_permlane16_swap_b32_e32 v32, v33
	v_cmp_gt_u32_e32 vcc, s24, v34
	v_add_f32_e32 v44, v44, v45
	v_add_f32_e32 v36, v36, v37
	v_add_f32_e32 v32, v32, v33
	v_cndmask_b32_e64 v35, 2, 1, vcc
	v_cmp_lt_i32_e32 vcc, s26, v160
	v_mov_b32_e32 v47, v46
	v_mov_b32_e32 v45, v44
	v_mov_b32_e32 v39, v38
	v_mov_b32_e32 v37, v36
	v_mov_b32_e32 v33, v32
	v_cndmask_b32_e32 v35, 0, v35, vcc
	v_permlane32_swap_b32_e32 v46, v47
	v_permlane32_swap_b32_e32 v44, v45
	v_permlane32_swap_b32_e32 v38, v39
	v_permlane32_swap_b32_e32 v36, v37
	v_permlane32_swap_b32_e32 v32, v33
	v_cmp_ne_u32_e32 vcc, v35, v96
	s_and_saveexec_b64 s[42:43], vcc
	s_cbranch_execz .LBB0_387
	v_mul_u32_u24_e32 v0, 0x7600, v35
	v_lshlrev_b32_e32 v96, 2, v0
	v_lshl_add_u64 v[0:1], s[44:45], 0, v[96:97]
	v_lshl_add_u64 v[12:13], v[154:155], 2, v[0:1]
	global_load_dwordx4 v[0:3], v[12:13], off offset:16
	global_load_dwordx4 v[4:7], v[12:13], off
	global_load_dwordx4 v[8:11], v[12:13], off offset:528
	s_nop 0
	global_load_dwordx4 v[12:15], v[12:13], off offset:512
	v_mov_b32_e32 v96, v35

.LBB0_465:
	s_add_u32 s58, s42, 0xfffd0080
	s_addc_u32 s59, s43, -1
	s_add_i32 s72, 0, 0x10000
	v_add_u32_e32 v96, s72, v163
	ds_read_b128 v[154:157], v96
	ds_read_b128 v[170:173], v96 offset:1024
	ds_read_b128 v[174:177], v96 offset:2048
	ds_read_b128 v[182:185], v96 offset:3072
	s_cmp_eq_u32 s71, 12
	s_cselect_b32 s61, s53, s59
	s_cselect_b32 s60, s52, s58
	s_cselect_b32 s59, s51, s70
	s_cselect_b32 s58, s68, s69
	v_lshl_add_u64 v[160:161], s[42:43], 0, v[150:151]
	s_add_i32 m0, s27, 0xc000
	ds_read_b128 v[186:189], v168
	ds_read_b128 v[190:193], v168 offset:1024
	ds_read_b128 v[194:197], v168 offset:2048
	ds_read_b128 v[198:201], v168 offset:3072
	ds_read_b128 v[224:227], v168 offset:4096
	ds_read_b128 v[228:231], v168 offset:5120
	global_load_lds_dwordx4 v[160:161], off
	v_lshl_add_u64 v[160:161], s[42:43], 0, v[152:153]
	s_add_i32 m0, s27, 0xe000
	s_mov_b64 exec, s[98:99]
	global_load_lds_dwordx4 v[160:161], off
	s_mov_b64 exec, -1
	s_waitcnt lgkmcnt(8)
	s_barrier
	s_waitcnt lgkmcnt(0)
	s_setprio 1
	s_waitcnt lgkmcnt(0)
	v_mfma_f32_16x16x32_bf16 v[134:137], v[154:157], v[186:189], v[134:137]
	v_mfma_f32_16x16x32_bf16 v[130:133], v[174:177], v[186:189], v[130:133]
	v_mfma_f32_16x16x32_bf16 v[92:95], v[154:157], v[194:197], v[92:95]
	v_mfma_f32_16x16x32_bf16 v[88:91], v[174:177], v[194:197], v[88:91]
	v_mfma_f32_16x16x32_bf16 v[76:79], v[154:157], v[224:227], v[76:79]
	v_mfma_f32_16x16x32_bf16 v[72:75], v[174:177], v[224:227], v[72:75]
	v_mfma_f32_16x16x32_bf16 v[134:137], v[170:173], v[190:193], v[134:137]
	v_mfma_f32_16x16x32_bf16 v[130:133], v[182:185], v[190:193], v[130:133]
	v_mfma_f32_16x16x32_bf16 v[92:95], v[170:173], v[198:201], v[92:95]
	v_mfma_f32_16x16x32_bf16 v[88:91], v[182:185], v[198:201], v[88:91]
	v_mfma_f32_16x16x32_bf16 v[76:79], v[170:173], v[228:231], v[76:79]
	v_mfma_f32_16x16x32_bf16 v[72:75], v[182:185], v[228:231], v[72:75]
	s_setprio 0
	s_barrier
	s_add_i32 s80, 0, 0x14000
	s_add_i32 s72, s72, s18
	v_add_u32_e32 v96, s80, v163
	v_lshl_add_u64 v[160:161], s[58:59], 0, v[140:141]
	s_mov_b32 m0, s72
	ds_read_b128 v[232:235], v96
	ds_read_b128 v[236:239], v96 offset:1024
	ds_read_b128 v[240:243], v96 offset:2048
	ds_read_b128 v[244:247], v96 offset:3072
	global_load_lds_dwordx4 v[160:161], off
	v_lshl_add_u64 v[164:165], s[58:59], 0, v[144:145]
	s_add_i32 m0, s72, 0x2000
	s_nop 0
	global_load_lds_dwordx4 v[164:165], off
	s_barrier
	s_waitcnt lgkmcnt(0)
	s_setprio 1
	s_waitcnt lgkmcnt(0)
	v_mfma_f32_16x16x32_bf16 v[110:113], v[232:235], v[186:189], v[110:113]
	v_mfma_f32_16x16x32_bf16 v[98:101], v[240:243], v[186:189], v[98:101]
	v_mfma_f32_16x16x32_bf16 v[84:87], v[232:235], v[194:197], v[84:87]
	s_mov_b32 m0, s27
	v_mfma_f32_16x16x32_bf16 v[80:83], v[240:243], v[194:197], v[80:83]
	v_lshl_add_u64 v[202:203], s[60:61], 0, v[138:139]
	v_mfma_f32_16x16x32_bf16 v[68:71], v[232:235], v[224:227], v[68:71]
	v_mfma_f32_16x16x32_bf16 v[64:67], v[240:243], v[224:227], v[64:67]
	v_mfma_f32_16x16x32_bf16 v[110:113], v[236:239], v[190:193], v[110:113]
	v_mfma_f32_16x16x32_bf16 v[98:101], v[244:247], v[190:193], v[98:101]
	v_mfma_f32_16x16x32_bf16 v[84:87], v[236:239], v[198:201], v[84:87]
	v_mfma_f32_16x16x32_bf16 v[80:83], v[244:247], v[198:201], v[80:83]
	v_mfma_f32_16x16x32_bf16 v[68:71], v[236:239], v[228:231], v[68:71]
	v_mfma_f32_16x16x32_bf16 v[64:67], v[244:247], v[228:231], v[64:67]
	s_setprio 0
	s_barrier
	ds_read_b128 v[186:189], v168 offset:16384
	ds_read_b128 v[190:193], v168 offset:17408
	ds_read_b128 v[194:197], v168 offset:18432
	ds_read_b128 v[198:201], v168 offset:19456
	ds_read_b128 v[224:227], v168 offset:20480
	ds_read_b128 v[228:231], v168 offset:21504
	global_load_lds_dwordx4 v[202:203], off
	v_lshl_add_u64 v[248:249], s[60:61], 0, v[142:143]
	s_mov_b32 m0, s28
	s_mov_b64 exec, s[98:99]
	global_load_lds_dwordx4 v[248:249], off
	s_mov_b64 exec, -1
	s_barrier
	s_waitcnt lgkmcnt(0)
	s_setprio 1
	s_waitcnt lgkmcnt(0)
	v_mfma_f32_16x16x32_bf16 v[60:63], v[154:157], v[186:189], v[60:63]
	v_mfma_f32_16x16x32_bf16 v[56:59], v[174:177], v[186:189], v[56:59]
	v_mfma_f32_16x16x32_bf16 v[44:47], v[154:157], v[194:197], v[44:47]
	v_mfma_f32_16x16x32_bf16 v[40:43], v[174:177], v[194:197], v[40:43]
	v_mfma_f32_16x16x32_bf16 v[28:31], v[154:157], v[224:227], v[28:31]
	v_mfma_f32_16x16x32_bf16 v[24:27], v[174:177], v[224:227], v[24:27]
	v_mfma_f32_16x16x32_bf16 v[60:63], v[170:173], v[190:193], v[60:63]
	v_mfma_f32_16x16x32_bf16 v[56:59], v[182:185], v[190:193], v[56:59]
	v_mfma_f32_16x16x32_bf16 v[44:47], v[170:173], v[198:201], v[44:47]
	v_mfma_f32_16x16x32_bf16 v[40:43], v[182:185], v[198:201], v[40:43]
	v_mfma_f32_16x16x32_bf16 v[28:31], v[170:173], v[228:231], v[28:31]
	v_mfma_f32_16x16x32_bf16 v[24:27], v[182:185], v[228:231], v[24:27]
	s_setprio 0
	s_barrier
	s_add_u32 s78, s58, 0x40000
	s_addc_u32 s79, s59, 0
	s_add_i32 s72, s80, s18
	v_lshl_add_u64 v[154:155], s[78:79], 0, v[140:141]
	s_mov_b32 m0, s72
	s_nop 0
	global_load_lds_dwordx4 v[154:155], off
	v_lshl_add_u64 v[154:155], s[78:79], 0, v[144:145]
	s_add_i32 m0, s72, 0x2000
	s_nop 0
	global_load_lds_dwordx4 v[154:155], off
	s_waitcnt vmcnt(6)
	s_barrier
	s_setprio 1
	v_mfma_f32_16x16x32_bf16 v[52:55], v[232:235], v[186:189], v[52:55]
	v_mfma_f32_16x16x32_bf16 v[48:51], v[240:243], v[186:189], v[48:51]
	v_mfma_f32_16x16x32_bf16 v[36:39], v[232:235], v[194:197], v[36:39]
	s_add_i32 s72, 0, 0x18000
	v_mfma_f32_16x16x32_bf16 v[32:35], v[240:243], v[194:197], v[32:35]
	v_add_u32_e32 v96, s72, v163
	v_mfma_f32_16x16x32_bf16 v[20:23], v[232:235], v[224:227], v[20:23]
	v_mfma_f32_16x16x32_bf16 v[16:19], v[240:243], v[224:227], v[16:19]
	v_mfma_f32_16x16x32_bf16 v[52:55], v[236:239], v[190:193], v[52:55]
	v_mfma_f32_16x16x32_bf16 v[48:51], v[244:247], v[190:193], v[48:51]
	v_mfma_f32_16x16x32_bf16 v[36:39], v[236:239], v[198:201], v[36:39]
	v_mfma_f32_16x16x32_bf16 v[32:35], v[244:247], v[198:201], v[32:35]
	v_mfma_f32_16x16x32_bf16 v[20:23], v[236:239], v[228:231], v[20:23]
	v_mfma_f32_16x16x32_bf16 v[16:19], v[244:247], v[228:231], v[16:19]
	s_setprio 0
	s_barrier
	ds_read_b128 v[154:157], v96
	ds_read_b128 v[170:173], v96 offset:1024
	ds_read_b128 v[174:177], v96 offset:2048
	ds_read_b128 v[182:185], v96 offset:3072
	s_add_u32 s60, s60, 0x30000
	s_addc_u32 s61, s61, 0
	s_mov_b32 m0, s37
	v_lshl_add_u64 v[232:233], s[60:61], 0, v[138:139]
	ds_read_b128 v[186:189], v168 offset:32768
	ds_read_b128 v[190:193], v168 offset:33792
	ds_read_b128 v[194:197], v168 offset:34816
	ds_read_b128 v[198:201], v168 offset:35840
	ds_read_b128 v[224:227], v168 offset:36864
	ds_read_b128 v[228:231], v168 offset:37888
	global_load_lds_dwordx4 v[232:233], off
	v_lshl_add_u64 v[232:233], s[60:61], 0, v[142:143]
	s_mov_b32 m0, s57
	s_mov_b64 exec, s[98:99]
	global_load_lds_dwordx4 v[232:233], off
	s_mov_b64 exec, -1
	s_waitcnt lgkmcnt(8)
	s_barrier
	s_waitcnt lgkmcnt(0)
	s_setprio 1
	s_waitcnt lgkmcnt(0)
	v_mfma_f32_16x16x32_bf16 v[134:137], v[154:157], v[186:189], v[134:137]
	v_mfma_f32_16x16x32_bf16 v[130:133], v[174:177], v[186:189], v[130:133]
	v_mfma_f32_16x16x32_bf16 v[92:95], v[154:157], v[194:197], v[92:95]
	v_mfma_f32_16x16x32_bf16 v[88:91], v[174:177], v[194:197], v[88:91]
	v_mfma_f32_16x16x32_bf16 v[76:79], v[154:157], v[224:227], v[76:79]
	v_mfma_f32_16x16x32_bf16 v[72:75], v[174:177], v[224:227], v[72:75]
	v_mfma_f32_16x16x32_bf16 v[134:137], v[170:173], v[190:193], v[134:137]
	v_mfma_f32_16x16x32_bf16 v[130:133], v[182:185], v[190:193], v[130:133]
	v_mfma_f32_16x16x32_bf16 v[92:95], v[170:173], v[198:201], v[92:95]
	v_mfma_f32_16x16x32_bf16 v[88:91], v[182:185], v[198:201], v[88:91]
	v_mfma_f32_16x16x32_bf16 v[76:79], v[170:173], v[228:231], v[76:79]
	v_mfma_f32_16x16x32_bf16 v[72:75], v[182:185], v[228:231], v[72:75]
	s_setprio 0
	s_barrier
	s_add_i32 s60, 0, 0x1c000
	s_add_i32 s61, s72, s18
	v_add_u32_e32 v96, s60, v163
	v_lshl_add_u64 v[160:161], v[160:161], 0, s[6:7]
	s_mov_b32 m0, s61
	ds_read_b128 v[232:235], v96
	ds_read_b128 v[236:239], v96 offset:1024
	ds_read_b128 v[240:243], v96 offset:2048
	ds_read_b128 v[244:247], v96 offset:3072
	global_load_lds_dwordx4 v[160:161], off
	v_lshl_add_u64 v[160:161], v[164:165], 0, s[6:7]
	s_add_i32 m0, s61, 0x2000
	s_nop 0
	global_load_lds_dwordx4 v[160:161], off
	s_barrier
	s_waitcnt lgkmcnt(0)
	s_setprio 1
	s_waitcnt lgkmcnt(0)
	v_mfma_f32_16x16x32_bf16 v[110:113], v[232:235], v[186:189], v[110:113]
	v_mfma_f32_16x16x32_bf16 v[98:101], v[240:243], v[186:189], v[98:101]
	v_mfma_f32_16x16x32_bf16 v[84:87], v[232:235], v[194:197], v[84:87]
	s_mov_b32 m0, s62
	v_mfma_f32_16x16x32_bf16 v[80:83], v[240:243], v[194:197], v[80:83]
	v_lshl_add_u64 v[160:161], v[202:203], 0, s[6:7]
	v_mfma_f32_16x16x32_bf16 v[68:71], v[232:235], v[224:227], v[68:71]
	v_mfma_f32_16x16x32_bf16 v[64:67], v[240:243], v[224:227], v[64:67]
	v_mfma_f32_16x16x32_bf16 v[110:113], v[236:239], v[190:193], v[110:113]
	v_mfma_f32_16x16x32_bf16 v[98:101], v[244:247], v[190:193], v[98:101]
	v_mfma_f32_16x16x32_bf16 v[84:87], v[236:239], v[198:201], v[84:87]
	v_mfma_f32_16x16x32_bf16 v[80:83], v[244:247], v[198:201], v[80:83]
	v_mfma_f32_16x16x32_bf16 v[68:71], v[236:239], v[228:231], v[68:71]
	v_mfma_f32_16x16x32_bf16 v[64:67], v[244:247], v[228:231], v[64:67]
	s_setprio 0
	s_barrier
	ds_read_b128 v[186:189], v168 offset:49152
	ds_read_b128 v[190:193], v168 offset:50176
	ds_read_b128 v[194:197], v168 offset:51200
	ds_read_b128 v[198:201], v168 offset:52224
	ds_read_b128 v[224:227], v168 offset:53248
	ds_read_b128 v[228:231], v168 offset:54272
	global_load_lds_dwordx4 v[160:161], off
	v_lshl_add_u64 v[160:161], v[248:249], 0, s[6:7]
	s_mov_b32 m0, s63
	s_mov_b64 exec, s[98:99]
	global_load_lds_dwordx4 v[160:161], off
	s_mov_b64 exec, -1
	s_barrier
	s_waitcnt lgkmcnt(0)
	s_setprio 1
	s_waitcnt lgkmcnt(0)
	v_mfma_f32_16x16x32_bf16 v[60:63], v[154:157], v[186:189], v[60:63]
	v_mfma_f32_16x16x32_bf16 v[56:59], v[174:177], v[186:189], v[56:59]
	v_mfma_f32_16x16x32_bf16 v[44:47], v[154:157], v[194:197], v[44:47]
	v_mfma_f32_16x16x32_bf16 v[40:43], v[174:177], v[194:197], v[40:43]
	v_mfma_f32_16x16x32_bf16 v[28:31], v[154:157], v[224:227], v[28:31]
	v_mfma_f32_16x16x32_bf16 v[24:27], v[174:177], v[224:227], v[24:27]
	v_mfma_f32_16x16x32_bf16 v[60:63], v[170:173], v[190:193], v[60:63]
	v_mfma_f32_16x16x32_bf16 v[56:59], v[182:185], v[190:193], v[56:59]
	v_mfma_f32_16x16x32_bf16 v[44:47], v[170:173], v[198:201], v[44:47]
	v_mfma_f32_16x16x32_bf16 v[40:43], v[182:185], v[198:201], v[40:43]
	v_mfma_f32_16x16x32_bf16 v[28:31], v[170:173], v[228:231], v[28:31]
	v_mfma_f32_16x16x32_bf16 v[24:27], v[182:185], v[228:231], v[24:27]
	s_setprio 0
	s_barrier
	s_add_u32 s58, s58, 0x40080
	s_addc_u32 s59, s59, 0
	s_add_i32 s60, s60, s18
	v_lshl_add_u64 v[154:155], s[58:59], 0, v[140:141]
	s_mov_b32 m0, s60
	s_nop 0
	global_load_lds_dwordx4 v[154:155], off
	v_lshl_add_u64 v[154:155], s[58:59], 0, v[144:145]
	s_add_i32 m0, s60, 0x2000
	s_nop 0
	global_load_lds_dwordx4 v[154:155], off
	s_waitcnt vmcnt(6)
	s_barrier
	s_setprio 1
	v_mfma_f32_16x16x32_bf16 v[52:55], v[232:235], v[186:189], v[52:55]
	v_mfma_f32_16x16x32_bf16 v[48:51], v[240:243], v[186:189], v[48:51]
	v_mfma_f32_16x16x32_bf16 v[36:39], v[232:235], v[194:197], v[36:39]
	s_add_i32 s71, s71, 2
	v_mfma_f32_16x16x32_bf16 v[32:35], v[240:243], v[194:197], v[32:35]
	s_add_u32 s42, s42, 0x100
	v_mfma_f32_16x16x32_bf16 v[20:23], v[232:235], v[224:227], v[20:23]
	s_addc_u32 s43, s43, 0
	v_mfma_f32_16x16x32_bf16 v[16:19], v[240:243], v[224:227], v[16:19]
	s_add_u32 s69, s69, 0x100
	v_mfma_f32_16x16x32_bf16 v[52:55], v[236:239], v[190:193], v[52:55]
	s_addc_u32 s70, s70, 0
	v_mfma_f32_16x16x32_bf16 v[48:51], v[244:247], v[190:193], v[48:51]
	s_cmp_gt_u32 s71, 13
	v_mfma_f32_16x16x32_bf16 v[36:39], v[236:239], v[198:201], v[36:39]
	v_mfma_f32_16x16x32_bf16 v[32:35], v[244:247], v[198:201], v[32:35]
	v_mfma_f32_16x16x32_bf16 v[20:23], v[236:239], v[228:231], v[20:23]
	v_mfma_f32_16x16x32_bf16 v[16:19], v[244:247], v[228:231], v[16:19]
	s_setprio 0
	s_barrier
	s_cbranch_scc0 .LBB0_465
	s_mul_i32 s42, s67, 0xc0
	s_add_i32 s42, s42, s19
	s_cmpk_lt_u32 s42, 0x2000
	s_cselect_b32 s43, 1, 2
	v_or_b32_e32 v156, s42, v159
	v_mov_b32_e32 v96, s43
	v_cmp_lt_i32_e32 vcc, s23, v156
	v_add_u32_e32 v160, 16, v156
	v_lshl_or_b32 v154, s56, 8, v166
	v_cndmask_b32_e32 v169, 0, v96, vcc
	s_waitcnt vmcnt(0)
	v_add_f32_e32 v96, v126, v127
	v_add_f32_e32 v126, v128, v129
	v_add_f32_e32 v96, v96, v126
	v_mov_b32_e32 v126, v96
	s_nop 1
	v_permlane16_swap_b32_e32 v96, v126
	v_add_f32_e32 v96, v96, v126
	v_mov_b32_e32 v126, v96
	s_nop 1
	v_permlane32_swap_b32_e32 v96, v126
	v_add_f32_e32 v96, v96, v126
	v_fmamk_f32 v96, v96, 0x3a800000, v207
	v_rsq_f32_e32 v162, v96
	v_add_f32_e32 v96, v122, v123
	v_add_f32_e32 v122, v124, v125
	v_add_f32_e32 v96, v96, v122
	v_mov_b32_e32 v122, v96
	s_nop 1
	v_permlane16_swap_b32_e32 v96, v122
	v_add_f32_e32 v96, v96, v122
	v_mov_b32_e32 v122, v96
	s_nop 1
	v_permlane32_swap_b32_e32 v96, v122
	v_add_f32_e32 v96, v96, v122
	v_fmamk_f32 v96, v96, 0x3a800000, v207
	v_rsq_f32_e32 v158, v96
	v_add_f32_e32 v96, v118, v119
	v_add_f32_e32 v118, v120, v121
	v_add_f32_e32 v96, v96, v118
	v_mov_b32_e32 v118, v96
	s_nop 1
	v_permlane16_swap_b32_e32 v96, v118
	v_add_f32_e32 v96, v96, v118
	v_mov_b32_e32 v118, v96
	s_nop 1
	v_permlane32_swap_b32_e32 v96, v118
	v_add_f32_e32 v96, v96, v118
	v_fmamk_f32 v96, v96, 0x3a800000, v207
	v_rsq_f32_e32 v128, v96
	v_add_f32_e32 v96, v114, v115
	v_add_f32_e32 v114, v116, v117
	v_add_f32_e32 v96, v96, v114
	v_mov_b32_e32 v114, v96
	s_nop 1
	v_permlane16_swap_b32_e32 v96, v114
	v_add_f32_e32 v96, v96, v114
	v_mov_b32_e32 v114, v96
	s_nop 1
	v_permlane32_swap_b32_e32 v96, v114
	v_add_f32_e32 v96, v96, v114
	v_fmamk_f32 v96, v96, 0x3a800000, v207
	v_rsq_f32_e32 v126, v96
	v_add_f32_e32 v96, v106, v107
	v_add_f32_e32 v106, v108, v109
	v_add_f32_e32 v96, v96, v106
	v_mov_b32_e32 v106, v96
	s_nop 1
	v_permlane16_swap_b32_e32 v96, v106
	v_add_f32_e32 v96, v96, v106
	v_mov_b32_e32 v106, v96
	s_nop 1
	v_permlane32_swap_b32_e32 v96, v106
	v_add_f32_e32 v96, v96, v106
	v_fmamk_f32 v96, v96, 0x3a800000, v207
	v_rsq_f32_e32 v124, v96
	v_add_f32_e32 v96, v102, v103
	v_add_f32_e32 v102, v104, v105
	v_add_f32_e32 v96, v96, v102
	v_mov_b32_e32 v102, v96
	s_nop 1
	v_permlane16_swap_b32_e32 v96, v102
	v_add_f32_e32 v96, v96, v102
	v_mov_b32_e32 v102, v96
	s_nop 1
	v_permlane32_swap_b32_e32 v96, v102
	v_add_f32_e32 v96, v96, v102
	v_fmamk_f32 v96, v96, 0x3a800000, v207
	v_rsq_f32_e32 v122, v96
	s_mov_b64 s[58:59], -1
	s_cmp_gt_i32 s56, 3
	v_ashrrev_i32_e32 v157, 31, v156
	v_cmp_lt_i32_e32 vcc, s26, v156
	v_cmp_gt_u32_e64 s[42:43], s24, v160
	s_cbranch_scc0 .LBB0_478
	v_lshlrev_b64 v[102:103], 11, v[156:157]
	v_lshl_add_u32 v96, s56, 7, v167
	v_lshl_add_u64 v[102:103], s[48:49], 0, v[102:103]
	v_lshl_add_u64 v[106:107], v[96:97], 1, v[102:103]
	v_pk_fma_f32 v[102:103], v[136:137], v[162:163], v[6:7] op_sel_hi:[1,0,1]
	v_pk_fma_f32 v[104:105], v[134:135], v[162:163], v[4:5] op_sel_hi:[1,0,1]
	v_pk_fma_f32 v[108:109], v[112:113], v[162:163], v[14:15] op_sel_hi:[1,0,1]
	v_pk_fma_f32 v[114:115], v[110:111], v[162:163], v[12:13] op_sel_hi:[1,0,1]
	v_pk_mul_f32 v[108:109], v[102:103], v[108:109]
	v_pk_mul_f32 v[102:103], v[104:105], v[114:115]
	v_pk_fma_f32 v[104:105], v[132:133], v[162:163], v[2:3] op_sel_hi:[1,0,1]
	v_pk_fma_f32 v[114:115], v[130:131], v[162:163], v[0:1] op_sel_hi:[1,0,1]
	v_pk_fma_f32 v[116:117], v[100:101], v[162:163], v[10:11] op_sel_hi:[1,0,1]
	v_pk_fma_f32 v[118:119], v[98:99], v[162:163], v[8:9] op_sel_hi:[1,0,1]
	v_pk_mul_f32 v[116:117], v[104:105], v[116:117]
	v_pk_mul_f32 v[104:105], v[114:115], v[118:119]
	v_cvt_pk_bf16_f32 v102, v102, v103
	v_cvt_pk_bf16_f32 v103, v108, v109
	v_mov_b64_e32 v[120:121], v[14:15]
	v_cvt_pk_bf16_f32 v104, v104, v105
	v_cvt_pk_bf16_f32 v105, v116, v117
	global_store_dwordx4 v[106:107], v[102:105], off
	v_mov_b64_e32 v[116:117], v[10:11]
	v_mov_b64_e32 v[108:109], v[6:7]
	v_cndmask_b32_e64 v102, 2, 1, s[42:43]
	v_cndmask_b32_e32 v125, 0, v102, vcc
	v_mov_b64_e32 v[104:105], v[2:3]
	v_mov_b32_e32 v155, v97
	v_cmp_ne_u32_e32 vcc, v125, v169
	v_mov_b64_e32 v[114:115], v[8:9]
	v_mov_b64_e32 v[102:103], v[0:1]
	v_mov_b64_e32 v[118:119], v[12:13]
	v_mov_b64_e32 v[106:107], v[4:5]
	v_mov_b32_e32 v123, v169
	s_and_saveexec_b64 s[42:43], vcc
	s_cbranch_execz .LBB0_469
	v_mul_u32_u24_e32 v102, 0x7600, v125
	v_lshlrev_b32_e32 v102, 2, v102
	v_mov_b32_e32 v103, v97
	v_lshl_add_u64 v[102:103], s[44:45], 0, v[102:103]
	v_lshl_add_u64 v[118:119], v[154:155], 2, v[102:103]
	global_load_dwordx4 v[102:105], v[118:119], off offset:16
	global_load_dwordx4 v[106:109], v[118:119], off
	global_load_dwordx4 v[114:117], v[118:119], off offset:528
	s_nop 0
	global_load_dwordx4 v[118:121], v[118:119], off offset:512
	v_mov_b32_e32 v123, v125

.LBB0_557:
	s_add_u32 s60, s58, 0xfffc0080
	s_addc_u32 s61, s59, -1
	s_add_i32 s72, 0, 0x10000
	v_add_u32_e32 v96, s72, v193
	ds_read_b128 v[80:83], v96
	ds_read_b128 v[88:91], v96 offset:1024
	ds_read_b128 v[102:105], v96 offset:2048
	ds_read_b128 v[106:109], v96 offset:3072
	s_cmp_eq_u32 s71, 12
	s_cselect_b32 s63, s49, s61
	s_cselect_b32 s62, s67, s60
	s_cselect_b32 s61, s47, s70
	s_cselect_b32 s60, s68, s69
	v_lshl_add_u64 v[176:177], s[58:59], 0, v[156:157]
	s_add_i32 m0, s27, 0xc000
	ds_read_b128 v[160:163], v195
	ds_read_b128 v[164:167], v195 offset:1024
	ds_read_b128 v[168:171], v195 offset:2048
	ds_read_b128 v[172:175], v195 offset:3072
	ds_read_b128 v[182:185], v195 offset:4096
	ds_read_b128 v[186:189], v195 offset:5120
	ds_read_b128 v[196:199], v195 offset:6144
	ds_read_b128 v[200:203], v195 offset:7168
	global_load_lds_dwordx4 v[176:177], off
	v_lshl_add_u64 v[176:177], s[58:59], 0, v[158:159]
	s_add_i32 m0, s27, 0xe000
	s_nop 0
	global_load_lds_dwordx4 v[176:177], off
	s_waitcnt lgkmcnt(8)
	s_barrier
	s_waitcnt lgkmcnt(0)
	s_setprio 1
	s_waitcnt lgkmcnt(0)
	v_mfma_f32_16x16x32_bf16 v[142:145], v[80:83], v[160:163], v[142:145]
	v_mfma_f32_16x16x32_bf16 v[138:141], v[102:105], v[160:163], v[138:141]
	v_mfma_f32_16x16x32_bf16 v[126:129], v[80:83], v[168:171], v[126:129]
	v_mfma_f32_16x16x32_bf16 v[122:125], v[102:105], v[168:171], v[122:125]
	v_mfma_f32_16x16x32_bf16 v[110:113], v[80:83], v[182:185], v[110:113]
	v_mfma_f32_16x16x32_bf16 v[98:101], v[102:105], v[182:185], v[98:101]
	v_mfma_f32_16x16x32_bf16 v[76:79], v[80:83], v[196:199], v[76:79]
	v_mfma_f32_16x16x32_bf16 v[72:75], v[102:105], v[196:199], v[72:75]
	v_mfma_f32_16x16x32_bf16 v[142:145], v[88:91], v[164:167], v[142:145]
	v_mfma_f32_16x16x32_bf16 v[138:141], v[106:109], v[164:167], v[138:141]
	v_mfma_f32_16x16x32_bf16 v[126:129], v[88:91], v[172:175], v[126:129]
	v_mfma_f32_16x16x32_bf16 v[122:125], v[106:109], v[172:175], v[122:125]
	v_mfma_f32_16x16x32_bf16 v[110:113], v[88:91], v[186:189], v[110:113]
	v_mfma_f32_16x16x32_bf16 v[98:101], v[106:109], v[186:189], v[98:101]
	v_mfma_f32_16x16x32_bf16 v[76:79], v[88:91], v[200:203], v[76:79]
	v_mfma_f32_16x16x32_bf16 v[72:75], v[106:109], v[200:203], v[72:75]
	s_setprio 0
	s_barrier
	s_add_i32 s76, 0, 0x14000
	s_add_i32 s72, s72, s18
	v_add_u32_e32 v96, s76, v193
	v_lshl_add_u64 v[176:177], s[60:61], 0, v[150:151]
	s_mov_b32 m0, s72
	ds_read_b128 v[224:227], v96
	ds_read_b128 v[228:231], v96 offset:1024
	ds_read_b128 v[232:235], v96 offset:2048
	ds_read_b128 v[236:239], v96 offset:3072
	global_load_lds_dwordx4 v[176:177], off
	v_lshl_add_u64 v[190:191], s[60:61], 0, v[146:147]
	s_add_i32 m0, s72, 0x2000
	s_nop 0
	global_load_lds_dwordx4 v[190:191], off
	s_barrier
	s_waitcnt lgkmcnt(0)
	s_setprio 1
	s_waitcnt lgkmcnt(0)
	v_mfma_f32_16x16x32_bf16 v[134:137], v[224:227], v[160:163], v[134:137]
	v_mfma_f32_16x16x32_bf16 v[130:133], v[232:235], v[160:163], v[130:133]
	v_mfma_f32_16x16x32_bf16 v[118:121], v[224:227], v[168:171], v[118:121]
	s_mov_b32 m0, s27
	v_mfma_f32_16x16x32_bf16 v[114:117], v[232:235], v[168:171], v[114:117]
	v_lshl_add_u64 v[240:241], s[62:63], 0, v[152:153]
	v_mfma_f32_16x16x32_bf16 v[92:95], v[224:227], v[182:185], v[92:95]
	v_mfma_f32_16x16x32_bf16 v[84:87], v[232:235], v[182:185], v[84:87]
	v_mfma_f32_16x16x32_bf16 v[68:71], v[224:227], v[196:199], v[68:71]
	v_mfma_f32_16x16x32_bf16 v[64:67], v[232:235], v[196:199], v[64:67]
	v_mfma_f32_16x16x32_bf16 v[134:137], v[228:231], v[164:167], v[134:137]
	v_mfma_f32_16x16x32_bf16 v[130:133], v[236:239], v[164:167], v[130:133]
	v_mfma_f32_16x16x32_bf16 v[118:121], v[228:231], v[172:175], v[118:121]
	v_mfma_f32_16x16x32_bf16 v[114:117], v[236:239], v[172:175], v[114:117]
	v_mfma_f32_16x16x32_bf16 v[92:95], v[228:231], v[186:189], v[92:95]
	v_mfma_f32_16x16x32_bf16 v[84:87], v[236:239], v[186:189], v[84:87]
	v_mfma_f32_16x16x32_bf16 v[68:71], v[228:231], v[200:203], v[68:71]
	v_mfma_f32_16x16x32_bf16 v[64:67], v[236:239], v[200:203], v[64:67]
	s_setprio 0
	s_barrier
	ds_read_b128 v[160:163], v195 offset:16384
	ds_read_b128 v[164:167], v195 offset:17408
	ds_read_b128 v[168:171], v195 offset:18432
	ds_read_b128 v[172:175], v195 offset:19456
	ds_read_b128 v[182:185], v195 offset:20480
	ds_read_b128 v[186:189], v195 offset:21504
	ds_read_b128 v[196:199], v195 offset:22528
	ds_read_b128 v[200:203], v195 offset:23552
	global_load_lds_dwordx4 v[240:241], off
	v_lshl_add_u64 v[242:243], s[62:63], 0, v[148:149]
	s_mov_b32 m0, s28
	s_nop 0
	global_load_lds_dwordx4 v[242:243], off
	s_barrier
	s_waitcnt lgkmcnt(0)
	s_setprio 1
	s_waitcnt lgkmcnt(0)
	v_mfma_f32_16x16x32_bf16 v[60:63], v[80:83], v[160:163], v[60:63]
	v_mfma_f32_16x16x32_bf16 v[56:59], v[102:105], v[160:163], v[56:59]
	v_mfma_f32_16x16x32_bf16 v[44:47], v[80:83], v[168:171], v[44:47]
	v_mfma_f32_16x16x32_bf16 v[40:43], v[102:105], v[168:171], v[40:43]
	v_mfma_f32_16x16x32_bf16 v[28:31], v[80:83], v[182:185], v[28:31]
	v_mfma_f32_16x16x32_bf16 v[24:27], v[102:105], v[182:185], v[24:27]
	v_mfma_f32_16x16x32_bf16 v[12:15], v[80:83], v[196:199], v[12:15]
	v_mfma_f32_16x16x32_bf16 v[8:11], v[102:105], v[196:199], v[8:11]
	v_mfma_f32_16x16x32_bf16 v[60:63], v[88:91], v[164:167], v[60:63]
	v_mfma_f32_16x16x32_bf16 v[56:59], v[106:109], v[164:167], v[56:59]
	v_mfma_f32_16x16x32_bf16 v[44:47], v[88:91], v[172:175], v[44:47]
	v_mfma_f32_16x16x32_bf16 v[40:43], v[106:109], v[172:175], v[40:43]
	v_mfma_f32_16x16x32_bf16 v[28:31], v[88:91], v[186:189], v[28:31]
	v_mfma_f32_16x16x32_bf16 v[24:27], v[106:109], v[186:189], v[24:27]
	v_mfma_f32_16x16x32_bf16 v[12:15], v[88:91], v[200:203], v[12:15]
	v_mfma_f32_16x16x32_bf16 v[8:11], v[106:109], v[200:203], v[8:11]
	s_setprio 0
	s_barrier
	s_add_u32 s74, s60, 0x40000
	s_addc_u32 s75, s61, 0
	s_add_i32 s72, s76, s18
	v_lshl_add_u64 v[80:81], s[74:75], 0, v[150:151]
	s_mov_b32 m0, s72
	s_nop 0
	global_load_lds_dwordx4 v[80:81], off
	v_lshl_add_u64 v[80:81], s[74:75], 0, v[146:147]
	s_add_i32 m0, s72, 0x2000
	s_nop 0
	global_load_lds_dwordx4 v[80:81], off
	s_waitcnt vmcnt(6)
	s_barrier
	s_setprio 1
	v_mfma_f32_16x16x32_bf16 v[52:55], v[224:227], v[160:163], v[52:55]
	v_mfma_f32_16x16x32_bf16 v[48:51], v[232:235], v[160:163], v[48:51]
	v_mfma_f32_16x16x32_bf16 v[36:39], v[224:227], v[168:171], v[36:39]
	s_add_i32 s72, 0, 0x18000
	v_mfma_f32_16x16x32_bf16 v[32:35], v[232:235], v[168:171], v[32:35]
	v_add_u32_e32 v96, s72, v193
	v_mfma_f32_16x16x32_bf16 v[20:23], v[224:227], v[182:185], v[20:23]
	v_mfma_f32_16x16x32_bf16 v[16:19], v[232:235], v[182:185], v[16:19]
	v_mfma_f32_16x16x32_bf16 v[4:7], v[224:227], v[196:199], v[4:7]
	v_mfma_f32_16x16x32_bf16 v[0:3], v[232:235], v[196:199], v[0:3]
	v_mfma_f32_16x16x32_bf16 v[52:55], v[228:231], v[164:167], v[52:55]
	v_mfma_f32_16x16x32_bf16 v[48:51], v[236:239], v[164:167], v[48:51]
	v_mfma_f32_16x16x32_bf16 v[36:39], v[228:231], v[172:175], v[36:39]
	v_mfma_f32_16x16x32_bf16 v[32:35], v[236:239], v[172:175], v[32:35]
	v_mfma_f32_16x16x32_bf16 v[20:23], v[228:231], v[186:189], v[20:23]
	v_mfma_f32_16x16x32_bf16 v[16:19], v[236:239], v[186:189], v[16:19]
	v_mfma_f32_16x16x32_bf16 v[4:7], v[228:231], v[200:203], v[4:7]
	v_mfma_f32_16x16x32_bf16 v[0:3], v[236:239], v[200:203], v[0:3]
	s_setprio 0
	s_barrier
	ds_read_b128 v[80:83], v96
	ds_read_b128 v[88:91], v96 offset:1024
	ds_read_b128 v[102:105], v96 offset:2048
	ds_read_b128 v[106:109], v96 offset:3072
	s_add_u32 s62, s62, 0x40000
	s_addc_u32 s63, s63, 0
	s_mov_b32 m0, s37
	v_lshl_add_u64 v[224:225], s[62:63], 0, v[152:153]
	ds_read_b128 v[160:163], v195 offset:32768
	ds_read_b128 v[164:167], v195 offset:33792
	ds_read_b128 v[168:171], v195 offset:34816
	ds_read_b128 v[172:175], v195 offset:35840
	ds_read_b128 v[182:185], v195 offset:36864
	ds_read_b128 v[186:189], v195 offset:37888
	ds_read_b128 v[196:199], v195 offset:38912
	ds_read_b128 v[200:203], v195 offset:39936
	global_load_lds_dwordx4 v[224:225], off
	v_lshl_add_u64 v[224:225], s[62:63], 0, v[148:149]
	s_mov_b32 m0, s56
	s_nop 0
	global_load_lds_dwordx4 v[224:225], off
	s_waitcnt lgkmcnt(8)
	s_barrier
	s_waitcnt lgkmcnt(0)
	s_setprio 1
	s_waitcnt lgkmcnt(0)
	v_mfma_f32_16x16x32_bf16 v[142:145], v[80:83], v[160:163], v[142:145]
	v_mfma_f32_16x16x32_bf16 v[138:141], v[102:105], v[160:163], v[138:141]
	v_mfma_f32_16x16x32_bf16 v[126:129], v[80:83], v[168:171], v[126:129]
	v_mfma_f32_16x16x32_bf16 v[122:125], v[102:105], v[168:171], v[122:125]
	v_mfma_f32_16x16x32_bf16 v[110:113], v[80:83], v[182:185], v[110:113]
	v_mfma_f32_16x16x32_bf16 v[98:101], v[102:105], v[182:185], v[98:101]
	v_mfma_f32_16x16x32_bf16 v[76:79], v[80:83], v[196:199], v[76:79]
	v_mfma_f32_16x16x32_bf16 v[72:75], v[102:105], v[196:199], v[72:75]
	v_mfma_f32_16x16x32_bf16 v[142:145], v[88:91], v[164:167], v[142:145]
	v_mfma_f32_16x16x32_bf16 v[138:141], v[106:109], v[164:167], v[138:141]
	v_mfma_f32_16x16x32_bf16 v[126:129], v[88:91], v[172:175], v[126:129]
	v_mfma_f32_16x16x32_bf16 v[122:125], v[106:109], v[172:175], v[122:125]
	v_mfma_f32_16x16x32_bf16 v[110:113], v[88:91], v[186:189], v[110:113]
	v_mfma_f32_16x16x32_bf16 v[98:101], v[106:109], v[186:189], v[98:101]
	v_mfma_f32_16x16x32_bf16 v[76:79], v[88:91], v[200:203], v[76:79]
	v_mfma_f32_16x16x32_bf16 v[72:75], v[106:109], v[200:203], v[72:75]
	s_setprio 0
	s_barrier
	s_add_i32 s62, 0, 0x1c000
	s_add_i32 s63, s72, s18
	v_add_u32_e32 v96, s62, v193
	v_lshl_add_u64 v[176:177], v[176:177], 0, s[6:7]
	s_mov_b32 m0, s63
	ds_read_b128 v[224:227], v96
	ds_read_b128 v[228:231], v96 offset:1024
	ds_read_b128 v[232:235], v96 offset:2048
	ds_read_b128 v[236:239], v96 offset:3072
	global_load_lds_dwordx4 v[176:177], off
	v_lshl_add_u64 v[176:177], v[190:191], 0, s[6:7]
	s_add_i32 m0, s63, 0x2000
	s_nop 0
	global_load_lds_dwordx4 v[176:177], off
	s_barrier
	s_waitcnt lgkmcnt(0)
	s_setprio 1
	s_waitcnt lgkmcnt(0)
	v_mfma_f32_16x16x32_bf16 v[134:137], v[224:227], v[160:163], v[134:137]
	v_mfma_f32_16x16x32_bf16 v[130:133], v[232:235], v[160:163], v[130:133]
	v_mfma_f32_16x16x32_bf16 v[118:121], v[224:227], v[168:171], v[118:121]
	s_mov_b32 m0, s64
	v_mfma_f32_16x16x32_bf16 v[114:117], v[232:235], v[168:171], v[114:117]
	v_lshl_add_u64 v[176:177], v[240:241], 0, s[6:7]
	v_mfma_f32_16x16x32_bf16 v[92:95], v[224:227], v[182:185], v[92:95]
	v_mfma_f32_16x16x32_bf16 v[84:87], v[232:235], v[182:185], v[84:87]
	v_mfma_f32_16x16x32_bf16 v[68:71], v[224:227], v[196:199], v[68:71]
	v_mfma_f32_16x16x32_bf16 v[64:67], v[232:235], v[196:199], v[64:67]
	v_mfma_f32_16x16x32_bf16 v[134:137], v[228:231], v[164:167], v[134:137]
	v_mfma_f32_16x16x32_bf16 v[130:133], v[236:239], v[164:167], v[130:133]
	v_mfma_f32_16x16x32_bf16 v[118:121], v[228:231], v[172:175], v[118:121]
	v_mfma_f32_16x16x32_bf16 v[114:117], v[236:239], v[172:175], v[114:117]
	v_mfma_f32_16x16x32_bf16 v[92:95], v[228:231], v[186:189], v[92:95]
	v_mfma_f32_16x16x32_bf16 v[84:87], v[236:239], v[186:189], v[84:87]
	v_mfma_f32_16x16x32_bf16 v[68:71], v[228:231], v[200:203], v[68:71]
	v_mfma_f32_16x16x32_bf16 v[64:67], v[236:239], v[200:203], v[64:67]
	s_setprio 0
	s_barrier
	ds_read_b128 v[160:163], v195 offset:49152
	ds_read_b128 v[164:167], v195 offset:50176
	ds_read_b128 v[168:171], v195 offset:51200
	ds_read_b128 v[172:175], v195 offset:52224
	ds_read_b128 v[182:185], v195 offset:53248
	ds_read_b128 v[186:189], v195 offset:54272
	ds_read_b128 v[196:199], v195 offset:55296
	ds_read_b128 v[200:203], v195 offset:56320
	global_load_lds_dwordx4 v[176:177], off
	v_lshl_add_u64 v[176:177], v[242:243], 0, s[6:7]
	s_mov_b32 m0, s65
	s_nop 0
	global_load_lds_dwordx4 v[176:177], off
	s_barrier
	s_waitcnt lgkmcnt(0)
	s_setprio 1
	s_waitcnt lgkmcnt(0)
	v_mfma_f32_16x16x32_bf16 v[60:63], v[80:83], v[160:163], v[60:63]
	v_mfma_f32_16x16x32_bf16 v[56:59], v[102:105], v[160:163], v[56:59]
	v_mfma_f32_16x16x32_bf16 v[44:47], v[80:83], v[168:171], v[44:47]
	v_mfma_f32_16x16x32_bf16 v[40:43], v[102:105], v[168:171], v[40:43]
	v_mfma_f32_16x16x32_bf16 v[28:31], v[80:83], v[182:185], v[28:31]
	v_mfma_f32_16x16x32_bf16 v[24:27], v[102:105], v[182:185], v[24:27]
	v_mfma_f32_16x16x32_bf16 v[12:15], v[80:83], v[196:199], v[12:15]
	v_mfma_f32_16x16x32_bf16 v[8:11], v[102:105], v[196:199], v[8:11]
	v_mfma_f32_16x16x32_bf16 v[60:63], v[88:91], v[164:167], v[60:63]
	v_mfma_f32_16x16x32_bf16 v[56:59], v[106:109], v[164:167], v[56:59]
	v_mfma_f32_16x16x32_bf16 v[44:47], v[88:91], v[172:175], v[44:47]
	v_mfma_f32_16x16x32_bf16 v[40:43], v[106:109], v[172:175], v[40:43]
	v_mfma_f32_16x16x32_bf16 v[28:31], v[88:91], v[186:189], v[28:31]
	v_mfma_f32_16x16x32_bf16 v[24:27], v[106:109], v[186:189], v[24:27]
	v_mfma_f32_16x16x32_bf16 v[12:15], v[88:91], v[200:203], v[12:15]
	v_mfma_f32_16x16x32_bf16 v[8:11], v[106:109], v[200:203], v[8:11]
	s_setprio 0
	s_barrier
	s_add_u32 s60, s60, 0x40080
	s_addc_u32 s61, s61, 0
	s_add_i32 s62, s62, s18
	v_lshl_add_u64 v[80:81], s[60:61], 0, v[150:151]
	s_mov_b32 m0, s62
	s_nop 0
	global_load_lds_dwordx4 v[80:81], off
	v_lshl_add_u64 v[80:81], s[60:61], 0, v[146:147]
	s_add_i32 m0, s62, 0x2000
	s_nop 0
	global_load_lds_dwordx4 v[80:81], off
	s_waitcnt vmcnt(6)
	s_barrier
	s_setprio 1
	v_mfma_f32_16x16x32_bf16 v[52:55], v[224:227], v[160:163], v[52:55]
	v_mfma_f32_16x16x32_bf16 v[48:51], v[232:235], v[160:163], v[48:51]
	v_mfma_f32_16x16x32_bf16 v[36:39], v[224:227], v[168:171], v[36:39]
	s_add_i32 s71, s71, 2
	v_mfma_f32_16x16x32_bf16 v[32:35], v[232:235], v[168:171], v[32:35]
	s_add_u32 s58, s58, 0x100
	v_mfma_f32_16x16x32_bf16 v[20:23], v[224:227], v[182:185], v[20:23]
	s_addc_u32 s59, s59, 0
	v_mfma_f32_16x16x32_bf16 v[16:19], v[232:235], v[182:185], v[16:19]
	s_add_u32 s69, s69, 0x100
	v_mfma_f32_16x16x32_bf16 v[4:7], v[224:227], v[196:199], v[4:7]
	s_addc_u32 s70, s70, 0
	v_mfma_f32_16x16x32_bf16 v[0:3], v[232:235], v[196:199], v[0:3]
	s_cmp_gt_u32 s71, 13
	v_mfma_f32_16x16x32_bf16 v[52:55], v[228:231], v[164:167], v[52:55]
	v_mfma_f32_16x16x32_bf16 v[48:51], v[236:239], v[164:167], v[48:51]
	v_mfma_f32_16x16x32_bf16 v[36:39], v[228:231], v[172:175], v[36:39]
	v_mfma_f32_16x16x32_bf16 v[32:35], v[236:239], v[172:175], v[32:35]
	v_mfma_f32_16x16x32_bf16 v[20:23], v[228:231], v[186:189], v[20:23]
	v_mfma_f32_16x16x32_bf16 v[16:19], v[236:239], v[186:189], v[16:19]
	v_mfma_f32_16x16x32_bf16 v[4:7], v[228:231], v[200:203], v[4:7]
	v_mfma_f32_16x16x32_bf16 v[0:3], v[236:239], v[200:203], v[0:3]
	s_setprio 0
	s_barrier
	s_cbranch_scc0 .LBB0_557
	s_lshl_b32 s47, s54, 8
	s_add_i32 s47, s47, s57
	v_or_b32_e32 v162, s47, v192
	v_ashrrev_i32_e32 v163, 31, v162
	v_or_b32_e32 v190, 16, v162
	v_lshlrev_b64 v[80:81], 6, v[162:163]
	v_ashrrev_i32_e32 v191, 31, v190
	v_or_b32_e32 v188, 32, v162
	v_lshl_add_u64 v[80:81], v[154:155], 0, v[80:81]
	v_lshlrev_b64 v[82:83], 6, v[190:191]
	v_ashrrev_i32_e32 v189, 31, v188
	v_lshl_add_u64 v[82:83], v[154:155], 0, v[82:83]
	global_load_dwordx4 v[174:177], v[80:81], off
	global_load_dwordx4 v[196:199], v[82:83], off
	v_lshlrev_b64 v[80:81], 6, v[188:189]
	v_or_b32_e32 v186, 48, v162
	v_lshl_add_u64 v[80:81], v[154:155], 0, v[80:81]
	v_ashrrev_i32_e32 v187, 31, v186
	global_load_dwordx4 v[200:203], v[80:81], off
	v_lshlrev_b64 v[80:81], 6, v[186:187]
	v_lshl_add_u64 v[80:81], v[154:155], 0, v[80:81]
	v_add_u32_e32 v184, 0x80, v162
	global_load_dwordx4 v[224:227], v[80:81], off
	v_ashrrev_i32_e32 v185, 31, v184
	v_lshlrev_b64 v[80:81], 6, v[184:185]
	v_lshl_add_u64 v[80:81], v[154:155], 0, v[80:81]
	global_load_dwordx4 v[228:231], v[80:81], off
	v_add_u32_e32 v172, 0x90, v162
	v_ashrrev_i32_e32 v173, 31, v172
	v_lshlrev_b64 v[80:81], 6, v[172:173]
	v_lshl_add_u64 v[80:81], v[154:155], 0, v[80:81]
	global_load_dwordx4 v[232:235], v[80:81], off
	v_add_u32_e32 v168, 0xa0, v162
	v_ashrrev_i32_e32 v169, 31, v168
	v_lshlrev_b64 v[80:81], 6, v[168:169]
	v_lshl_add_u64 v[80:81], v[154:155], 0, v[80:81]
	global_load_dwordx4 v[236:239], v[80:81], off
	v_add_u32_e32 v164, 0xb0, v162
	v_ashrrev_i32_e32 v165, 31, v164
	v_lshlrev_b64 v[80:81], 6, v[164:165]
	s_cmpk_lt_u32 s47, 0x2000
	v_lshl_add_u64 v[80:81], v[154:155], 0, v[80:81]
	s_cselect_b32 s47, 1, 2
	global_load_dwordx4 v[240:243], v[80:81], off
	v_mov_b32_e32 v218, s47
	v_cmp_lt_i32_e32 vcc, s23, v162
	v_lshl_or_b32 v166, s55, 8, v194
	v_ashrrev_i32_e32 v167, 31, v166
	v_cndmask_b32_e32 v185, 0, v218, vcc
	v_mul_u32_u24_e32 v82, 0x7600, v185
	v_lshlrev_b32_e32 v96, 2, v82
	v_lshl_add_u64 v[80:81], s[44:45], 0, v[96:97]
	v_lshl_add_u64 v[106:107], v[166:167], 2, v[80:81]
	global_load_dwordx4 v[80:83], v[106:107], off offset:16
	global_load_dwordx4 v[88:91], v[106:107], off
	global_load_dwordx4 v[102:105], v[106:107], off offset:528
	s_nop 0
	global_load_dwordx4 v[106:109], v[106:107], off offset:512
	v_lshl_or_b32 v160, s55, 7, v194
	v_cmp_lt_i32_e32 vcc, s23, v190
	s_waitcnt vmcnt(0)
	v_add_f32_e32 v96, v174, v175
	v_add_f32_e32 v161, v176, v177
	v_add_f32_e32 v96, v96, v161
	v_add_f32_e32 v161, v196, v197
	v_add_f32_e32 v163, v198, v199
	v_add_f32_e32 v161, v161, v163
	v_add_f32_e32 v165, v200, v201
	v_add_f32_e32 v169, v202, v203
	v_add_f32_e32 v163, v165, v169
	v_mov_b32_e32 v169, v161
	v_add_f32_e32 v170, v224, v225
	v_add_f32_e32 v171, v226, v227
	v_add_f32_e32 v165, v170, v171
	v_mov_b32_e32 v170, v163
	v_permlane16_swap_b32_e32 v161, v169
	s_nop 0
	v_permlane16_swap_b32_e32 v163, v170
	v_add_f32_e32 v201, v161, v169
	v_add_f32_e32 v199, v163, v170
	v_add_f32_e32 v161, v228, v229
	v_add_f32_e32 v163, v230, v231
	v_add_f32_e32 v161, v161, v163
	v_mov_b32_e32 v163, v161
	s_nop 1
	v_permlane16_swap_b32_e32 v161, v163
	v_add_f32_e32 v191, v161, v163
	v_add_f32_e32 v161, v232, v233
	v_add_f32_e32 v163, v234, v235
	v_add_f32_e32 v161, v161, v163
	v_mov_b32_e32 v173, v96
	v_mov_b32_e32 v163, v161
	s_nop 0
	v_permlane16_swap_b32_e32 v96, v173
	v_permlane16_swap_b32_e32 v161, v163
	v_add_f32_e32 v96, v96, v173
	v_add_f32_e32 v187, v161, v163
	v_add_f32_e32 v161, v236, v237
	v_add_f32_e32 v163, v238, v239
	v_mov_b32_e32 v173, v96
	v_add_f32_e32 v161, v161, v163
	s_nop 0
	v_permlane32_swap_b32_e32 v96, v173
	v_mov_b32_e32 v163, v161
	v_add_f32_e32 v96, v96, v173
	s_nop 0
	v_permlane16_swap_b32_e32 v161, v163
	v_fmamk_f32 v96, v96, 0x3a800000, v207
	v_add_f32_e32 v169, v161, v163
	v_add_f32_e32 v161, v240, v241
	v_add_f32_e32 v163, v242, v243
	v_mov_b32_e32 v171, v165
	v_rsq_f32_e32 v96, v96
	v_add_f32_e32 v161, v161, v163
	v_permlane16_swap_b32_e32 v165, v171
	v_mov_b32_e32 v163, v161
	v_add_f32_e32 v197, v165, v171
	s_nop 0
	v_permlane16_swap_b32_e32 v161, v163
	v_mov_b64_e32 v[170:171], s[42:43]
	v_add_f32_e32 v163, v161, v163
	v_ashrrev_i32_e32 v161, 31, v160
	v_mad_i64_i32 v[170:171], s[54:55], v162, s31, v[170:171]
	v_lshl_add_u64 v[224:225], v[160:161], 1, v[170:171]
	v_pk_mul_f32 v[182:183], v[82:83], s[0:1] op_sel_hi:[1,0]
	v_pk_mul_f32 v[176:177], v[80:81], s[0:1] op_sel_hi:[1,0]
	v_pk_mul_f32 v[174:175], v[90:91], s[0:1] op_sel_hi:[1,0]
	v_pk_mul_f32 v[170:171], v[88:89], s[0:1] op_sel_hi:[1,0]
	v_mul_f32_e32 v226, 0xbfb8aa3b, v96
	v_pk_fma_f32 v[228:229], v[144:145], v[226:227], v[174:175] op_sel_hi:[1,0,1]
	v_pk_fma_f32 v[230:231], v[142:143], v[226:227], v[170:171] op_sel_hi:[1,0,1]
	v_pk_fma_f32 v[232:233], v[140:141], v[226:227], v[182:183] op_sel_hi:[1,0,1]
	v_pk_fma_f32 v[226:227], v[138:139], v[226:227], v[176:177] op_sel_hi:[1,0,1]
	v_exp_f32_e32 v230, v230
	v_exp_f32_e32 v226, v226
	v_exp_f32_e32 v231, v231
	v_exp_f32_e32 v227, v227
	v_exp_f32_e32 v232, v232
	v_exp_f32_e32 v233, v233
	v_exp_f32_e32 v228, v228
	v_exp_f32_e32 v229, v229
	v_pk_add_f32 v[230:231], v[230:231], 1.0 op_sel_hi:[1,0]
	v_pk_add_f32 v[232:233], v[232:233], 1.0 op_sel_hi:[1,0]
	v_pk_add_f32 v[226:227], v[226:227], 1.0 op_sel_hi:[1,0]
	v_pk_add_f32 v[228:229], v[228:229], 1.0 op_sel_hi:[1,0]
	v_rcp_f32_e32 v230, v230
	v_rcp_f32_e32 v226, v226
	v_rcp_f32_e32 v231, v231
	v_rcp_f32_e32 v227, v227
	v_rcp_f32_e32 v232, v232
	v_rcp_f32_e32 v233, v233
	v_rcp_f32_e32 v228, v228
	v_rcp_f32_e32 v229, v229
	v_pk_fma_f32 v[142:143], v[142:143], v[96:97], v[88:89] op_sel_hi:[1,0,1]
	v_pk_fma_f32 v[140:141], v[140:141], v[96:97], v[82:83] op_sel_hi:[1,0,1]
	v_pk_fma_f32 v[138:139], v[138:139], v[96:97], v[80:81] op_sel_hi:[1,0,1]
	v_pk_fma_f32 v[134:135], v[134:135], v[96:97], v[106:107] op_sel_hi:[1,0,1]
	v_pk_fma_f32 v[132:133], v[132:133], v[96:97], v[104:105] op_sel_hi:[1,0,1]
	v_pk_fma_f32 v[130:131], v[130:131], v[96:97], v[102:103] op_sel_hi:[1,0,1]
	v_pk_fma_f32 v[144:145], v[144:145], v[96:97], v[90:91] op_sel_hi:[1,0,1]
	v_pk_fma_f32 v[136:137], v[136:137], v[96:97], v[108:109] op_sel_hi:[1,0,1]
	v_pk_mul_f32 v[134:135], v[142:143], v[134:135]
	v_pk_mul_f32 v[132:133], v[140:141], v[132:133]
	v_pk_mul_f32 v[130:131], v[138:139], v[130:131]
	v_pk_mul_f32 v[136:137], v[144:145], v[136:137]
	v_pk_mul_f32 v[134:135], v[134:135], v[230:231]
	v_pk_mul_f32 v[138:139], v[132:133], v[232:233]
	v_pk_mul_f32 v[132:133], v[130:131], v[226:227]
	v_cvt_pk_bf16_f32 v130, v134, v135
	v_mov_b32_e32 v202, v201
	v_mov_b32_e32 v200, v199
	v_mov_b32_e32 v198, v197
	v_mov_b32_e32 v196, v191
	v_mov_b32_e32 v189, v187
	v_mov_b32_e32 v173, v169
	v_mov_b32_e32 v165, v163
	v_pk_mul_f32 v[136:137], v[136:137], v[228:229]
	v_permlane32_swap_b32_e32 v201, v202
	v_cvt_pk_bf16_f32 v131, v136, v137
	v_cvt_pk_bf16_f32 v132, v132, v133
	v_cvt_pk_bf16_f32 v133, v138, v139
	global_store_dwordx4 v[224:225], v[130:133], off
	v_permlane32_swap_b32_e32 v199, v200
	s_nop 0
	v_cndmask_b32_e32 v130, 0, v218, vcc
	v_permlane32_swap_b32_e32 v197, v198
	v_permlane32_swap_b32_e32 v191, v196
	v_permlane32_swap_b32_e32 v187, v189
	v_permlane32_swap_b32_e32 v169, v173
	v_permlane32_swap_b32_e32 v163, v165
	v_cmp_ne_u32_e32 vcc, v130, v185
	s_and_saveexec_b64 s[54:55], vcc
	s_cbranch_execz .LBB0_560
	v_mul_u32_u24_e32 v80, 0x7600, v130
	v_lshlrev_b32_e32 v96, 2, v80
	v_lshl_add_u64 v[80:81], s[44:45], 0, v[96:97]
	v_lshl_add_u64 v[106:107], v[166:167], 2, v[80:81]
	global_load_dwordx4 v[88:91], v[106:107], off
	global_load_dwordx4 v[80:83], v[106:107], off offset:16
	global_load_dwordx4 v[102:105], v[106:107], off offset:528
	s_nop 0
	global_load_dwordx4 v[106:109], v[106:107], off offset:512
	v_mov_b32_e32 v185, v130
	s_waitcnt vmcnt(0)
	v_pk_mul_f32 v[170:171], v[88:89], s[0:1] op_sel_hi:[1,0]
	v_pk_mul_f32 v[174:175], v[90:91], s[0:1] op_sel_hi:[1,0]
	v_pk_mul_f32 v[176:177], v[80:81], s[0:1] op_sel_hi:[1,0]
	v_pk_mul_f32 v[182:183], v[82:83], s[0:1] op_sel_hi:[1,0]

.LBB0_1021:
	s_add_i32 vcc_hi, s46, 2
	s_add_u32 s84, s44, 0x80
	s_addc_u32 s47, s45, 0
	s_add_i32 s29, 0, 0x10000
	v_add_u32_e32 v96, s29, v225
	ds_read_b128 v[56:59], v96
	ds_read_b128 v[68:71], v96 offset:1024
	ds_read_b128 v[80:83], v96 offset:2048
	ds_read_b128 v[98:101], v96 offset:3072
	s_cmp_eq_u32 s90, s46
	s_cselect_b32 s46, s80, s84
	s_cselect_b32 s47, s81, s47
	s_cselect_b32 s85, s83, vcc_lo
	s_cselect_b32 s84, s82, s87
	v_lshl_add_u64 v[106:107], s[44:45], 0, v[188:189]
	s_add_i32 m0, s2, 0xc000
	ds_read_b128 v[102:105], v227
	ds_read_b128 v[112:115], v227 offset:1024
	ds_read_b128 v[124:127], v227 offset:2048
	ds_read_b128 v[192:195], v227 offset:3072
	ds_read_b128 v[196:199], v227 offset:4096
	ds_read_b128 v[200:203], v227 offset:5120
	global_load_lds_dwordx4 v[106:107], off
	v_lshl_add_u64 v[106:107], s[44:45], 0, v[190:191]
	s_add_i32 m0, s2, 0xe000
	s_mov_b64 exec, s[98:99]
	global_load_lds_dwordx4 v[106:107], off
	s_mov_b64 exec, -1
	s_waitcnt lgkmcnt(8)
	s_barrier
	s_waitcnt lgkmcnt(0)
	s_setprio 1
	s_waitcnt lgkmcnt(0)
	v_mfma_f32_16x16x32_bf16 v[172:175], v[56:59], v[102:105], v[172:175]
	v_mfma_f32_16x16x32_bf16 v[168:171], v[80:83], v[102:105], v[168:171]
	v_mfma_f32_16x16x32_bf16 v[156:159], v[56:59], v[124:127], v[156:159]
	v_mfma_f32_16x16x32_bf16 v[152:155], v[80:83], v[124:127], v[152:155]
	v_mfma_f32_16x16x32_bf16 v[132:135], v[56:59], v[196:199], v[132:135]
	v_mfma_f32_16x16x32_bf16 v[128:131], v[80:83], v[196:199], v[128:131]
	v_mfma_f32_16x16x32_bf16 v[172:175], v[68:71], v[112:115], v[172:175]
	v_mfma_f32_16x16x32_bf16 v[168:171], v[98:101], v[112:115], v[168:171]
	v_mfma_f32_16x16x32_bf16 v[156:159], v[68:71], v[192:195], v[156:159]
	v_mfma_f32_16x16x32_bf16 v[152:155], v[98:101], v[192:195], v[152:155]
	v_mfma_f32_16x16x32_bf16 v[132:135], v[68:71], v[200:203], v[132:135]
	v_mfma_f32_16x16x32_bf16 v[128:131], v[98:101], v[200:203], v[128:131]
	s_setprio 0
	s_barrier
	s_add_i32 s96, 0, 0x14000
	s_add_i32 s29, s29, s18
	v_add_u32_e32 v96, s96, v225
	v_lshl_add_u64 v[106:107], s[84:85], 0, v[182:183]
	s_mov_b32 m0, s29
	ds_read_b128 v[228:231], v96
	ds_read_b128 v[232:235], v96 offset:1024
	ds_read_b128 v[236:239], v96 offset:2048
	ds_read_b128 v[240:243], v96 offset:3072
	global_load_lds_dwordx4 v[106:107], off
	v_lshl_add_u64 v[248:249], s[84:85], 0, v[186:187]
	s_add_i32 m0, s29, 0x2000
	s_nop 0
	global_load_lds_dwordx4 v[248:249], off
	s_barrier
	s_waitcnt lgkmcnt(0)
	s_setprio 1
	s_waitcnt lgkmcnt(0)
	v_mfma_f32_16x16x32_bf16 v[164:167], v[228:231], v[102:105], v[164:167]
	v_mfma_f32_16x16x32_bf16 v[102:105], v[236:239], v[102:105], v[160:163]
	v_mfma_f32_16x16x32_bf16 v[120:123], v[228:231], v[196:199], v[120:123]
	s_mov_b32 m0, s2
	v_mfma_f32_16x16x32_bf16 v[116:119], v[236:239], v[196:199], v[116:119]
	v_lshl_add_u64 v[250:251], s[46:47], 0, v[176:177]
	v_mfma_f32_16x16x32_bf16 v[164:167], v[232:235], v[112:115], v[164:167]
	v_mfma_f32_16x16x32_bf16 v[102:105], v[240:243], v[112:115], v[102:105]
	v_mfma_f32_16x16x32_bf16 v[112:115], v[228:231], v[124:127], v[148:151]
	v_mfma_f32_16x16x32_bf16 v[124:127], v[236:239], v[124:127], v[144:147]
	v_mfma_f32_16x16x32_bf16 v[120:123], v[232:235], v[200:203], v[120:123]
	v_mfma_f32_16x16x32_bf16 v[116:119], v[240:243], v[200:203], v[116:119]
	v_mfma_f32_16x16x32_bf16 v[112:115], v[232:235], v[192:195], v[112:115]
	v_mfma_f32_16x16x32_bf16 v[124:127], v[240:243], v[192:195], v[124:127]
	s_setprio 0
	s_barrier
	ds_read_b128 v[144:147], v227 offset:16384
	ds_read_b128 v[148:151], v227 offset:17408
	ds_read_b128 v[160:163], v227 offset:18432
	ds_read_b128 v[192:195], v227 offset:19456
	ds_read_b128 v[196:199], v227 offset:20480
	ds_read_b128 v[200:203], v227 offset:21504
	global_load_lds_dwordx4 v[250:251], off
	v_lshl_add_u64 v[252:253], s[46:47], 0, v[184:185]
	s_mov_b32 m0, s3
	s_mov_b64 exec, s[98:99]
	global_load_lds_dwordx4 v[252:253], off
	s_mov_b64 exec, -1
	s_barrier
	s_waitcnt lgkmcnt(0)
	s_setprio 1
	s_waitcnt lgkmcnt(0)
	v_mfma_f32_16x16x32_bf16 v[88:91], v[56:59], v[144:147], v[88:91]
	v_mfma_f32_16x16x32_bf16 v[84:87], v[80:83], v[144:147], v[84:87]
	v_mfma_f32_16x16x32_bf16 v[52:55], v[56:59], v[160:163], v[52:55]
	v_mfma_f32_16x16x32_bf16 v[48:51], v[80:83], v[160:163], v[48:51]
	v_mfma_f32_16x16x32_bf16 v[28:31], v[56:59], v[196:199], v[28:31]
	v_mfma_f32_16x16x32_bf16 v[24:27], v[80:83], v[196:199], v[24:27]
	v_mfma_f32_16x16x32_bf16 v[88:91], v[68:71], v[148:151], v[88:91]
	v_mfma_f32_16x16x32_bf16 v[84:87], v[98:101], v[148:151], v[84:87]
	v_mfma_f32_16x16x32_bf16 v[52:55], v[68:71], v[192:195], v[52:55]
	v_mfma_f32_16x16x32_bf16 v[48:51], v[98:101], v[192:195], v[48:51]
	v_mfma_f32_16x16x32_bf16 v[28:31], v[68:71], v[200:203], v[28:31]
	v_mfma_f32_16x16x32_bf16 v[24:27], v[98:101], v[200:203], v[24:27]
	s_setprio 0
	s_barrier
	s_add_u32 s84, s84, s57
	s_addc_u32 s85, s85, 0
	s_add_i32 s29, s96, s18
	v_lshl_add_u64 v[218:219], s[84:85], 0, v[182:183]
	s_mov_b32 m0, s29
	v_lshl_add_u64 v[220:221], s[84:85], 0, v[186:187]
	global_load_lds_dwordx4 v[218:219], off
	s_add_i32 m0, s29, 0x2000
	s_nop 0
	global_load_lds_dwordx4 v[220:221], off
	s_waitcnt vmcnt(6)
	s_barrier
	s_setprio 1
	v_mfma_f32_16x16x32_bf16 v[44:47], v[228:231], v[160:163], v[44:47]
	v_mfma_f32_16x16x32_bf16 v[40:43], v[236:239], v[160:163], v[40:43]
	v_mfma_f32_16x16x32_bf16 v[20:23], v[228:231], v[196:199], v[20:23]
	s_add_i32 s29, 0, 0x18000
	v_mfma_f32_16x16x32_bf16 v[16:19], v[236:239], v[196:199], v[16:19]
	v_add_u32_e32 v96, s29, v225
	v_mfma_f32_16x16x32_bf16 v[56:59], v[228:231], v[144:147], v[76:79]
	v_mfma_f32_16x16x32_bf16 v[68:71], v[236:239], v[144:147], v[72:75]
	v_mfma_f32_16x16x32_bf16 v[44:47], v[232:235], v[192:195], v[44:47]
	v_mfma_f32_16x16x32_bf16 v[40:43], v[240:243], v[192:195], v[40:43]
	v_mfma_f32_16x16x32_bf16 v[20:23], v[232:235], v[200:203], v[20:23]
	v_mfma_f32_16x16x32_bf16 v[16:19], v[240:243], v[200:203], v[16:19]
	v_mfma_f32_16x16x32_bf16 v[56:59], v[232:235], v[148:151], v[56:59]
	v_mfma_f32_16x16x32_bf16 v[68:71], v[240:243], v[148:151], v[68:71]
	s_setprio 0
	s_barrier
	ds_read_b128 v[72:75], v96
	ds_read_b128 v[76:79], v96 offset:1024
	ds_read_b128 v[80:83], v96 offset:2048
	ds_read_b128 v[98:101], v96 offset:3072
	s_add_u32 s46, s46, s64
	s_addc_u32 s47, s47, 0
	s_mov_b32 m0, s4
	v_lshl_add_u64 v[160:161], s[46:47], 0, v[176:177]
	ds_read_b128 v[144:147], v227 offset:32768
	ds_read_b128 v[148:151], v227 offset:33792
	ds_read_b128 v[192:195], v227 offset:34816
	ds_read_b128 v[196:199], v227 offset:35840
	ds_read_b128 v[200:203], v227 offset:36864
	ds_read_b128 v[228:231], v227 offset:37888
	global_load_lds_dwordx4 v[160:161], off
	v_lshl_add_u64 v[160:161], s[46:47], 0, v[184:185]
	s_mov_b32 m0, s5
	s_mov_b64 exec, s[98:99]
	global_load_lds_dwordx4 v[160:161], off
	s_mov_b64 exec, -1
	s_waitcnt lgkmcnt(8)
	s_barrier
	s_waitcnt lgkmcnt(0)
	s_setprio 1
	s_waitcnt lgkmcnt(0)
	v_mfma_f32_16x16x32_bf16 v[160:163], v[72:75], v[144:147], v[172:175]
	v_mfma_f32_16x16x32_bf16 v[172:175], v[76:79], v[148:151], v[160:163]
	v_mfma_f32_16x16x32_bf16 v[160:163], v[80:83], v[144:147], v[168:171]
	v_mfma_f32_16x16x32_bf16 v[156:159], v[72:75], v[192:195], v[156:159]
	v_mfma_f32_16x16x32_bf16 v[152:155], v[80:83], v[192:195], v[152:155]
	v_mfma_f32_16x16x32_bf16 v[132:135], v[72:75], v[200:203], v[132:135]
	v_mfma_f32_16x16x32_bf16 v[128:131], v[80:83], v[200:203], v[128:131]
	v_mfma_f32_16x16x32_bf16 v[168:171], v[98:101], v[148:151], v[160:163]
	v_mfma_f32_16x16x32_bf16 v[156:159], v[76:79], v[196:199], v[156:159]
	v_mfma_f32_16x16x32_bf16 v[152:155], v[98:101], v[196:199], v[152:155]
	v_mfma_f32_16x16x32_bf16 v[132:135], v[76:79], v[228:231], v[132:135]
	v_mfma_f32_16x16x32_bf16 v[128:131], v[98:101], v[228:231], v[128:131]
	s_setprio 0
	s_barrier
	s_add_i32 s46, 0, 0x1c000
	s_add_i32 s29, s29, s18
	v_add_u32_e32 v96, s46, v225
	v_lshl_add_u64 v[106:107], v[106:107], 0, s[6:7]
	s_mov_b32 m0, s29
	ds_read_b128 v[232:235], v96
	ds_read_b128 v[236:239], v96 offset:1024
	ds_read_b128 v[240:243], v96 offset:2048
	ds_read_b128 v[244:247], v96 offset:3072
	global_load_lds_dwordx4 v[106:107], off
	v_lshl_add_u64 v[106:107], v[248:249], 0, s[6:7]
	s_add_i32 m0, s29, 0x2000
	s_nop 0
	global_load_lds_dwordx4 v[106:107], off
	s_barrier
	s_waitcnt lgkmcnt(0)
	s_setprio 1
	s_waitcnt lgkmcnt(0)
	v_mfma_f32_16x16x32_bf16 v[160:163], v[232:235], v[144:147], v[164:167]
	v_mfma_f32_16x16x32_bf16 v[102:105], v[240:243], v[144:147], v[102:105]
	v_mfma_f32_16x16x32_bf16 v[164:167], v[236:239], v[148:151], v[160:163]
	s_mov_b32 m0, s88
	v_mfma_f32_16x16x32_bf16 v[160:163], v[244:247], v[148:151], v[102:105]
	v_lshl_add_u64 v[106:107], v[250:251], 0, s[6:7]
	v_mfma_f32_16x16x32_bf16 v[102:105], v[232:235], v[192:195], v[112:115]
	v_mfma_f32_16x16x32_bf16 v[148:151], v[236:239], v[196:199], v[102:105]
	v_mfma_f32_16x16x32_bf16 v[102:105], v[240:243], v[192:195], v[124:127]
	v_mfma_f32_16x16x32_bf16 v[144:147], v[244:247], v[196:199], v[102:105]
	v_mfma_f32_16x16x32_bf16 v[102:105], v[232:235], v[200:203], v[120:123]
	v_mfma_f32_16x16x32_bf16 v[120:123], v[236:239], v[228:231], v[102:105]
	v_mfma_f32_16x16x32_bf16 v[102:105], v[240:243], v[200:203], v[116:119]
	v_mfma_f32_16x16x32_bf16 v[116:119], v[244:247], v[228:231], v[102:105]
	s_setprio 0
	s_barrier
	s_nop 2
	ds_read_b128 v[102:105], v227 offset:49152
	ds_read_b128 v[112:115], v227 offset:50176
	ds_read_b128 v[124:127], v227 offset:51200
	ds_read_b128 v[192:195], v227 offset:52224
	ds_read_b128 v[196:199], v227 offset:53248
	ds_read_b128 v[200:203], v227 offset:54272
	global_load_lds_dwordx4 v[106:107], off
	v_lshl_add_u64 v[106:107], v[252:253], 0, s[6:7]
	s_mov_b32 m0, s89
	s_mov_b64 exec, s[98:99]
	global_load_lds_dwordx4 v[106:107], off
	s_mov_b64 exec, -1
	s_barrier
	s_waitcnt lgkmcnt(0)
	s_setprio 1
	s_waitcnt lgkmcnt(0)
	v_mfma_f32_16x16x32_bf16 v[88:91], v[72:75], v[102:105], v[88:91]
	v_mfma_f32_16x16x32_bf16 v[84:87], v[80:83], v[102:105], v[84:87]
	v_mfma_f32_16x16x32_bf16 v[52:55], v[72:75], v[124:127], v[52:55]
	v_mfma_f32_16x16x32_bf16 v[48:51], v[80:83], v[124:127], v[48:51]
	v_mfma_f32_16x16x32_bf16 v[28:31], v[72:75], v[196:199], v[28:31]
	v_mfma_f32_16x16x32_bf16 v[24:27], v[80:83], v[196:199], v[24:27]
	v_mfma_f32_16x16x32_bf16 v[88:91], v[76:79], v[112:115], v[88:91]
	v_mfma_f32_16x16x32_bf16 v[84:87], v[98:101], v[112:115], v[84:87]
	v_mfma_f32_16x16x32_bf16 v[52:55], v[76:79], v[192:195], v[52:55]
	v_mfma_f32_16x16x32_bf16 v[48:51], v[98:101], v[192:195], v[48:51]
	v_mfma_f32_16x16x32_bf16 v[28:31], v[76:79], v[200:203], v[28:31]
	v_mfma_f32_16x16x32_bf16 v[24:27], v[98:101], v[200:203], v[24:27]
	s_setprio 0
	s_barrier
	s_add_i32 s29, s46, s18
	v_lshl_add_u64 v[72:73], v[218:219], 0, s[6:7]
	s_mov_b32 m0, s29
	s_nop 0
	global_load_lds_dwordx4 v[72:73], off
	v_lshl_add_u64 v[72:73], v[220:221], 0, s[6:7]
	s_add_i32 m0, s29, 0x2000
	s_nop 0
	global_load_lds_dwordx4 v[72:73], off
	s_waitcnt vmcnt(6)
	s_barrier
	s_setprio 1
	v_mfma_f32_16x16x32_bf16 v[56:59], v[232:235], v[102:105], v[56:59]
	v_mfma_f32_16x16x32_bf16 v[76:79], v[236:239], v[112:115], v[56:59]
	v_mfma_f32_16x16x32_bf16 v[56:59], v[240:243], v[102:105], v[68:71]
	s_add_u32 s44, s44, 0x100
	v_mfma_f32_16x16x32_bf16 v[44:47], v[232:235], v[124:127], v[44:47]
	s_addc_u32 s45, s45, 0
	v_mfma_f32_16x16x32_bf16 v[40:43], v[240:243], v[124:127], v[40:43]
	s_add_u32 s87, s87, 0x100
	v_mfma_f32_16x16x32_bf16 v[20:23], v[232:235], v[196:199], v[20:23]
	s_addc_u32 vcc_lo, vcc_lo, 0
	v_mfma_f32_16x16x32_bf16 v[16:19], v[240:243], v[196:199], v[16:19]
	s_cmp_ge_u32 vcc_hi, s37
	v_mfma_f32_16x16x32_bf16 v[72:75], v[244:247], v[112:115], v[56:59]
	s_mov_b32 s46, vcc_hi
	v_mfma_f32_16x16x32_bf16 v[44:47], v[236:239], v[192:195], v[44:47]
	v_mfma_f32_16x16x32_bf16 v[40:43], v[244:247], v[192:195], v[40:43]
	v_mfma_f32_16x16x32_bf16 v[20:23], v[236:239], v[200:203], v[20:23]
	v_mfma_f32_16x16x32_bf16 v[16:19], v[244:247], v[200:203], v[16:19]
	s_setprio 0
	s_barrier
	s_cbranch_scc0 .LBB0_1021
	s_mul_i32 s44, s86, 0xc0
	s_add_i32 s44, s44, s19
	s_cmpk_lt_u32 s44, 0x2000
	v_or_b32_e32 v198, s44, v223
	s_cselect_b32 s44, 1, 2
	v_mov_b32_e32 v56, s44
	v_cmp_lt_i32_e32 vcc, s23, v198
	v_lshl_or_b32 v192, s72, 8, v226
	v_ashrrev_i32_e32 v193, 31, v192
	v_cndmask_b32_e32 v228, 0, v56, vcc
	v_mul_u32_u24_e32 v56, 0x1800, v228
	v_lshlrev_b32_e32 v96, 2, v56
	v_lshl_add_u64 v[56:57], s[70:71], 0, v[96:97]
	v_lshlrev_b64 v[68:69], 2, v[192:193]
	v_lshl_add_u64 v[124:125], v[56:57], 0, v[68:69]
	global_load_dwordx4 v[56:59], v[124:125], off
	v_cndmask_b32_e64 v70, 0, 1, s[78:79]
	v_cmp_ne_u32_e64 s[46:47], 1, v70
	s_andn2_b64 vcc, exec, s[78:79]
	v_lshl_add_u64 v[196:197], s[54:55], 0, v[68:69]
	s_cbranch_vccnz .LBB0_1024
	global_load_dwordx4 v[80:83], v[196:197], off
	s_waitcnt vmcnt(0)
	v_pk_mul_f32 v[58:59], v[58:59], v[82:83]
	v_pk_mul_f32 v[56:57], v[56:57], v[80:81]
